# speedup vs baseline: 1.0147x; 1.0147x over previous
; #define PG8_STAGE(bufoff, gbase, voff) do { _Pragma("unroll") for (int _i = 0; _i < 2; ++_i) \
;         __builtin_amdgcn_global_load_lds((const unsigned*)((const char*)(gbase) + (voff)[_i]), (PG8_LAS unsigned*)(lds + (bufoff) + ldsw + _i * 8192), 16, 0, 0); } while (0)
; #define PG8_LDA(dst, b, h) do { _Pragma("unroll") for (int m = 0; m < 4; ++m) _Pragma("unroll") for (int k = 0; k < 2; ++k) dst[m][k] = *(const PG8_LAS bf16x8*)(lds + PG8_SA(b, h) + aoff + m * 2048 + k * 1024); } while (0)
; #define PG8_LDB(dst, b, h) do { _Pragma("unroll") for (int n = 0; n < 2; ++n) _Pragma("unroll") for (int k = 0; k < 2; ++k) dst[n][k] = *(const PG8_LAS bf16x8*)(lds + PG8_SB(b, h) + boff + n * 2048 + k * 1024); } while (0)
; #define PG8_MMA(ai, bj, At, Bt) do { __builtin_amdgcn_s_setprio(1); _Pragma("unroll") for (int m = 0; m < 4; ++m) _Pragma("unroll") for (int n = 0; n < 2; ++n) _Pragma("unroll") for (int k = 0; k < 2; ++k) \
;         acc[ai][bj][m][n] = __builtin_amdgcn_mfma_f32_16x16x32_bf16(Bt[n][k], At[m][k], acc[ai][bj][m][n], 0, 0, 0); __builtin_amdgcn_s_setprio(0); } while (0)
; #define PG8_WAIT_V(n) asm volatile("s_waitcnt vmcnt(" #n ")" ::: "memory")
; #define PG8_WAIT_L(n) asm volatile("s_waitcnt lgkmcnt(" #n ")" ::: "memory")
; template <class Epi, class Sched, bool ALIGN_EPI = false, bool SP2 = false>
; __device__ __forceinline__ void gemm_phase(PG8_LAS unsigned char* lds, const Gemm g, const Sched& S, const Epi& E, const int wv) {
;     ...
;             const bool last = (t == nt - 2);
;             const char* a1 = cA + (size_t)(t + 1) * kstep;
;             const char* a2 = last ? nA : cA + (size_t)(t + 2) * kstep; const char* b2 = last ? nB : cB + (size_t)(t + 2) * kstep;
;             const char* a3 = a2 + kstep; const char* b3 = b2 + kstep;
;             if (last && has_next) S.a_ready(nxt);
;             if constexpr (SP2) {
;             PG8_LDB(B0, 0, 0); PG8_LDB(B1, 0, 1); PG8_SCHED; PG8_LDA(At, 0, 0); PG8_STAGE(PG8_SA(1, 1), a1 + hstep, voffA);
;             PG8_WAIT_V(8); PG8_WAIT_L(0); PG8_BAR; PG8_MMA(0, 0, At, B0); PG8_MMA(0, 1, At, B1); PG8_BAR; PG8_SCHED;
;             PG8_LDA(At, 0, 1); PG8_STAGE(PG8_SB(0, 0), b2, voffB); PG8_STAGE(PG8_SB(0, 1), b2 + hstep, voffB); PG8_STAGE(PG8_SA(0, 0), a2, voffA);
;             PG8_WAIT_V(8); PG8_WAIT_L(0); PG8_BAR; PG8_MMA(1, 0, At, B0); PG8_MMA(1, 1, At, B1); PG8_BAR; PG8_SCHED;
.LBB0_134:
	s_add_u32 s26, s24, 0xfffc0080
	s_addc_u32 s27, s25, -1
	s_add_i32 s51, 0, 0x10000
	s_cmp_eq_u32 s50, 12
	s_cselect_b32 s29, s17, s27
	s_cselect_b32 s28, s23, s26
	v_add_u32_e32 v0, s51, v183
	s_cselect_b32 s27, s15, s49
	s_cselect_b32 s26, s33, s48
	s_add_i32 s54, 0, 0x14000
	ds_read_b128 v[142:145], v0
	ds_read_b128 v[146:149], v0 offset:1024
	ds_read_b128 v[150:153], v0 offset:2048
	ds_read_b128 v[154:157], v0 offset:3072
	v_add_u32_e32 v0, s54, v183
	ds_read_b128 v[158:161], v0
	ds_read_b128 v[162:165], v0 offset:1024
	ds_read_b128 v[166:169], v0 offset:2048
	ds_read_b128 v[170:173], v0 offset:3072
	v_lshl_add_u64 v[208:209], s[24:25], 0, v[138:139]
	s_add_i32 m0, s39, 0xc000
	ds_read_b128 v[174:177], v186
	ds_read_b128 v[178:181], v186 offset:1024
	ds_read_b128 v[188:191], v186 offset:2048
	ds_read_b128 v[192:195], v186 offset:3072
	ds_read_b128 v[196:199], v186 offset:4096
	ds_read_b128 v[200:203], v186 offset:5120
	ds_read_b128 v[204:207], v186 offset:6144
	ds_read_b128 v[218:221], v186 offset:7168
	global_load_lds_dwordx4 v[208:209], off
	v_lshl_add_u64 v[208:209], s[24:25], 0, v[140:141]
	s_add_i32 m0, s39, 0xe000
	s_nop 0
	global_load_lds_dwordx4 v[208:209], off
	s_waitcnt vmcnt(8)
	s_waitcnt lgkmcnt(0)
	s_barrier
	s_setprio 1
	s_waitcnt lgkmcnt(0)
	v_mfma_f32_16x16x32_bf16 v[126:129], v[142:145], v[174:177], v[126:129]
	v_mfma_f32_16x16x32_bf16 v[122:125], v[150:153], v[174:177], v[122:125]
	v_mfma_f32_16x16x32_bf16 v[110:113], v[142:145], v[188:191], v[110:113]
	v_mfma_f32_16x16x32_bf16 v[106:109], v[150:153], v[188:191], v[106:109]
	v_mfma_f32_16x16x32_bf16 v[94:97], v[142:145], v[196:199], v[94:97]
	v_mfma_f32_16x16x32_bf16 v[90:93], v[150:153], v[196:199], v[90:93]
	v_mfma_f32_16x16x32_bf16 v[78:81], v[142:145], v[204:207], v[78:81]
	v_mfma_f32_16x16x32_bf16 v[74:77], v[150:153], v[204:207], v[74:77]
	v_mfma_f32_16x16x32_bf16 v[126:129], v[146:149], v[178:181], v[126:129]
	v_mfma_f32_16x16x32_bf16 v[122:125], v[154:157], v[178:181], v[122:125]
	v_mfma_f32_16x16x32_bf16 v[110:113], v[146:149], v[192:195], v[110:113]
	v_mfma_f32_16x16x32_bf16 v[106:109], v[154:157], v[192:195], v[106:109]
	v_mfma_f32_16x16x32_bf16 v[94:97], v[146:149], v[200:203], v[94:97]
	v_mfma_f32_16x16x32_bf16 v[90:93], v[154:157], v[200:203], v[90:93]
	v_mfma_f32_16x16x32_bf16 v[78:81], v[146:149], v[218:221], v[78:81]
	v_mfma_f32_16x16x32_bf16 v[74:77], v[154:157], v[218:221], v[74:77]
	s_setprio 0
	s_setprio 1
	v_mfma_f32_16x16x32_bf16 v[118:121], v[158:161], v[174:177], v[118:121]
	v_mfma_f32_16x16x32_bf16 v[114:117], v[166:169], v[174:177], v[114:117]
	v_mfma_f32_16x16x32_bf16 v[102:105], v[158:161], v[188:191], v[102:105]
	v_mfma_f32_16x16x32_bf16 v[98:101], v[166:169], v[188:191], v[98:101]
	v_mfma_f32_16x16x32_bf16 v[86:89], v[158:161], v[196:199], v[86:89]
	v_mfma_f32_16x16x32_bf16 v[82:85], v[166:169], v[196:199], v[82:85]
	v_mfma_f32_16x16x32_bf16 v[70:73], v[158:161], v[204:207], v[70:73]
	v_mfma_f32_16x16x32_bf16 v[66:69], v[166:169], v[204:207], v[66:69]
	v_mfma_f32_16x16x32_bf16 v[118:121], v[162:165], v[178:181], v[118:121]
	v_mfma_f32_16x16x32_bf16 v[114:117], v[170:173], v[178:181], v[114:117]
	v_mfma_f32_16x16x32_bf16 v[102:105], v[162:165], v[192:195], v[102:105]
	v_mfma_f32_16x16x32_bf16 v[98:101], v[170:173], v[192:195], v[98:101]
	v_mfma_f32_16x16x32_bf16 v[86:89], v[162:165], v[200:203], v[86:89]
	v_mfma_f32_16x16x32_bf16 v[82:85], v[170:173], v[200:203], v[82:85]
	v_mfma_f32_16x16x32_bf16 v[70:73], v[162:165], v[218:221], v[70:73]
	v_mfma_f32_16x16x32_bf16 v[66:69], v[170:173], v[218:221], v[66:69]
	s_barrier
	s_setprio 0
	s_add_i32 s51, s51, s35
	v_lshl_add_u64 v[208:209], s[26:27], 0, v[134:135]
	s_mov_b32 m0, s51
	ds_read_b128 v[174:177], v186 offset:16384
	ds_read_b128 v[178:181], v186 offset:17408
	ds_read_b128 v[188:191], v186 offset:18432
	ds_read_b128 v[192:195], v186 offset:19456
	ds_read_b128 v[196:199], v186 offset:20480
	ds_read_b128 v[200:203], v186 offset:21504
	ds_read_b128 v[204:207], v186 offset:22528
	ds_read_b128 v[218:221], v186 offset:23552
	global_load_lds_dwordx4 v[208:209], off
	s_add_i32 m0, s51, 0x2000
	s_add_u32 s52, s26, 0x40000
	v_lshl_add_u64 v[210:211], s[26:27], 0, v[130:131]
	s_addc_u32 s53, s27, 0
	s_add_i32 s51, s54, s35
	global_load_lds_dwordx4 v[210:211], off
	v_lshl_add_u64 v[212:213], s[52:53], 0, v[134:135]
	s_mov_b32 m0, s51
	v_lshl_add_u64 v[214:215], s[28:29], 0, v[132:133]
	global_load_lds_dwordx4 v[212:213], off
	v_lshl_add_u64 v[212:213], s[52:53], 0, v[130:131]
	s_add_i32 m0, s51, 0x2000
	s_nop 0
	global_load_lds_dwordx4 v[212:213], off
	v_lshl_add_u64 v[212:213], s[28:29], 0, v[136:137]
	s_mov_b32 m0, s39
	s_nop 0
	global_load_lds_dwordx4 v[212:213], off
	s_mov_b32 m0, s40
	s_nop 0
	global_load_lds_dwordx4 v[214:215], off
	s_waitcnt vmcnt(8)
	s_waitcnt lgkmcnt(0)
	s_barrier
; #define PG8_STAGE(bufoff, gbase, voff) do { _Pragma("unroll") for (int _i = 0; _i < 2; ++_i) \
;         __builtin_amdgcn_global_load_lds((const unsigned*)((const char*)(gbase) + (voff)[_i]), (PG8_LAS unsigned*)(lds + (bufoff) + ldsw + _i * 8192), 16, 0, 0); } while (0)
; #define PG8_LDA(dst, b, h) do { _Pragma("unroll") for (int m = 0; m < 4; ++m) _Pragma("unroll") for (int k = 0; k < 2; ++k) dst[m][k] = *(const PG8_LAS bf16x8*)(lds + PG8_SA(b, h) + aoff + m * 2048 + k * 1024); } while (0)
; #define PG8_LDB(dst, b, h) do { _Pragma("unroll") for (int n = 0; n < 2; ++n) _Pragma("unroll") for (int k = 0; k < 2; ++k) dst[n][k] = *(const PG8_LAS bf16x8*)(lds + PG8_SB(b, h) + boff + n * 2048 + k * 1024); } while (0)
; #define PG8_MMA(ai, bj, At, Bt) do { __builtin_amdgcn_s_setprio(1); _Pragma("unroll") for (int m = 0; m < 4; ++m) _Pragma("unroll") for (int n = 0; n < 2; ++n) _Pragma("unroll") for (int k = 0; k < 2; ++k) \
;         acc[ai][bj][m][n] = __builtin_amdgcn_mfma_f32_16x16x32_bf16(Bt[n][k], At[m][k], acc[ai][bj][m][n], 0, 0, 0); __builtin_amdgcn_s_setprio(0); } while (0)
; #define PG8_WAIT_V(n) asm volatile("s_waitcnt vmcnt(" #n ")" ::: "memory")
; #define PG8_WAIT_L(n) asm volatile("s_waitcnt lgkmcnt(" #n ")" ::: "memory")
; #define PG8_BAR __builtin_amdgcn_s_barrier()
; #define PG8_SCHED __builtin_amdgcn_sched_barrier(0)
; template <class Epi, class Sched, bool ALIGN_EPI = false, bool SP2 = false>
; __device__ __forceinline__ void gemm_phase(PG8_LAS unsigned char* lds, const Gemm g, const Sched& S, const Epi& E, const int wv) {
;     ...
;             PG8_WAIT_V(8); PG8_WAIT_L(0); PG8_BAR; PG8_MMA(1, 0, At, B0); PG8_MMA(1, 1, At, B1); PG8_BAR; PG8_SCHED;
;             PG8_LDB(B0, 1, 0); PG8_LDB(B1, 1, 1); PG8_SCHED; PG8_LDA(At, 1, 0); PG8_STAGE(PG8_SA(0, 1), a2 + hstep, voffA);
;             PG8_WAIT_V(8); PG8_WAIT_L(0); PG8_BAR; PG8_MMA(0, 0, At, B0); PG8_MMA(0, 1, At, B1); PG8_BAR; PG8_SCHED;
	s_setprio 1
	s_waitcnt lgkmcnt(0)
	v_mfma_f32_16x16x32_bf16 v[62:65], v[142:145], v[174:177], v[62:65]
	v_mfma_f32_16x16x32_bf16 v[58:61], v[150:153], v[174:177], v[58:61]
	v_mfma_f32_16x16x32_bf16 v[46:49], v[142:145], v[188:191], v[46:49]
	v_mfma_f32_16x16x32_bf16 v[42:45], v[150:153], v[188:191], v[42:45]
	v_mfma_f32_16x16x32_bf16 v[30:33], v[142:145], v[196:199], v[30:33]
	v_mfma_f32_16x16x32_bf16 v[26:29], v[150:153], v[196:199], v[26:29]
	v_mfma_f32_16x16x32_bf16 v[14:17], v[142:145], v[204:207], v[14:17]
	v_mfma_f32_16x16x32_bf16 v[10:13], v[150:153], v[204:207], v[10:13]
	v_mfma_f32_16x16x32_bf16 v[62:65], v[146:149], v[178:181], v[62:65]
	v_mfma_f32_16x16x32_bf16 v[58:61], v[154:157], v[178:181], v[58:61]
	v_mfma_f32_16x16x32_bf16 v[46:49], v[146:149], v[192:195], v[46:49]
	v_mfma_f32_16x16x32_bf16 v[42:45], v[154:157], v[192:195], v[42:45]
	v_mfma_f32_16x16x32_bf16 v[30:33], v[146:149], v[200:203], v[30:33]
	v_mfma_f32_16x16x32_bf16 v[26:29], v[154:157], v[200:203], v[26:29]
	v_mfma_f32_16x16x32_bf16 v[14:17], v[146:149], v[218:221], v[14:17]
	v_mfma_f32_16x16x32_bf16 v[10:13], v[154:157], v[218:221], v[10:13]
	s_setprio 0
	s_setprio 1
	v_mfma_f32_16x16x32_bf16 v[54:57], v[158:161], v[174:177], v[54:57]
	v_mfma_f32_16x16x32_bf16 v[50:53], v[166:169], v[174:177], v[50:53]
	v_mfma_f32_16x16x32_bf16 v[38:41], v[158:161], v[188:191], v[38:41]
	v_mfma_f32_16x16x32_bf16 v[34:37], v[166:169], v[188:191], v[34:37]
	v_mfma_f32_16x16x32_bf16 v[22:25], v[158:161], v[196:199], v[22:25]
	v_mfma_f32_16x16x32_bf16 v[18:21], v[166:169], v[196:199], v[18:21]
	v_mfma_f32_16x16x32_bf16 v[6:9], v[158:161], v[204:207], v[6:9]
	v_mfma_f32_16x16x32_bf16 v[2:5], v[166:169], v[204:207], v[2:5]
	v_mfma_f32_16x16x32_bf16 v[54:57], v[162:165], v[178:181], v[54:57]
	v_mfma_f32_16x16x32_bf16 v[50:53], v[170:173], v[178:181], v[50:53]
	v_mfma_f32_16x16x32_bf16 v[38:41], v[162:165], v[192:195], v[38:41]
	v_mfma_f32_16x16x32_bf16 v[34:37], v[170:173], v[192:195], v[34:37]
	v_mfma_f32_16x16x32_bf16 v[22:25], v[162:165], v[200:203], v[22:25]
	v_mfma_f32_16x16x32_bf16 v[18:21], v[170:173], v[200:203], v[18:21]
	v_mfma_f32_16x16x32_bf16 v[6:9], v[162:165], v[218:221], v[6:9]
	v_mfma_f32_16x16x32_bf16 v[2:5], v[170:173], v[218:221], v[2:5]
	s_barrier
	s_setprio 0
	s_add_i32 s51, 0, 0x18000
	v_add_u32_e32 v0, s51, v183
	s_add_i32 s52, 0, 0x1c000
	ds_read_b128 v[142:145], v0
	ds_read_b128 v[146:149], v0 offset:1024
	ds_read_b128 v[150:153], v0 offset:2048
	ds_read_b128 v[154:157], v0 offset:3072
	v_add_u32_e32 v0, s52, v183
	ds_read_b128 v[158:161], v0
	ds_read_b128 v[162:165], v0 offset:1024
	ds_read_b128 v[166:169], v0 offset:2048
	ds_read_b128 v[170:173], v0 offset:3072
	s_add_u32 s28, s28, 0x40000
	s_addc_u32 s29, s29, 0
	s_mov_b32 m0, s41
	v_lshl_add_u64 v[216:217], s[28:29], 0, v[136:137]
	ds_read_b128 v[174:177], v186 offset:32768
	ds_read_b128 v[178:181], v186 offset:33792
	ds_read_b128 v[188:191], v186 offset:34816
	ds_read_b128 v[192:195], v186 offset:35840
	ds_read_b128 v[196:199], v186 offset:36864
	ds_read_b128 v[200:203], v186 offset:37888
	ds_read_b128 v[204:207], v186 offset:38912
	ds_read_b128 v[218:221], v186 offset:39936
	global_load_lds_dwordx4 v[216:217], off
	v_lshl_add_u64 v[216:217], s[28:29], 0, v[132:133]
	s_mov_b32 m0, s42
	s_nop 0
	global_load_lds_dwordx4 v[216:217], off
	s_waitcnt vmcnt(8)
	s_waitcnt lgkmcnt(0)
	s_barrier
	s_setprio 1
	s_waitcnt lgkmcnt(0)
	v_mfma_f32_16x16x32_bf16 v[126:129], v[142:145], v[174:177], v[126:129]
	v_mfma_f32_16x16x32_bf16 v[122:125], v[150:153], v[174:177], v[122:125]
	v_mfma_f32_16x16x32_bf16 v[110:113], v[142:145], v[188:191], v[110:113]
	v_mfma_f32_16x16x32_bf16 v[106:109], v[150:153], v[188:191], v[106:109]
	v_mfma_f32_16x16x32_bf16 v[94:97], v[142:145], v[196:199], v[94:97]
	v_mfma_f32_16x16x32_bf16 v[90:93], v[150:153], v[196:199], v[90:93]
	v_mfma_f32_16x16x32_bf16 v[78:81], v[142:145], v[204:207], v[78:81]
	v_mfma_f32_16x16x32_bf16 v[74:77], v[150:153], v[204:207], v[74:77]
	v_mfma_f32_16x16x32_bf16 v[126:129], v[146:149], v[178:181], v[126:129]
	v_mfma_f32_16x16x32_bf16 v[122:125], v[154:157], v[178:181], v[122:125]
	v_mfma_f32_16x16x32_bf16 v[110:113], v[146:149], v[192:195], v[110:113]
	v_mfma_f32_16x16x32_bf16 v[106:109], v[154:157], v[192:195], v[106:109]
	v_mfma_f32_16x16x32_bf16 v[94:97], v[146:149], v[200:203], v[94:97]
	v_mfma_f32_16x16x32_bf16 v[90:93], v[154:157], v[200:203], v[90:93]
	v_mfma_f32_16x16x32_bf16 v[78:81], v[146:149], v[218:221], v[78:81]
	v_mfma_f32_16x16x32_bf16 v[74:77], v[154:157], v[218:221], v[74:77]
	s_setprio 0
	s_setprio 1
	v_mfma_f32_16x16x32_bf16 v[118:121], v[158:161], v[174:177], v[118:121]
	v_mfma_f32_16x16x32_bf16 v[114:117], v[166:169], v[174:177], v[114:117]
	v_mfma_f32_16x16x32_bf16 v[102:105], v[158:161], v[188:191], v[102:105]
	v_mfma_f32_16x16x32_bf16 v[98:101], v[166:169], v[188:191], v[98:101]
	v_mfma_f32_16x16x32_bf16 v[86:89], v[158:161], v[196:199], v[86:89]
	v_mfma_f32_16x16x32_bf16 v[82:85], v[166:169], v[196:199], v[82:85]
	v_mfma_f32_16x16x32_bf16 v[70:73], v[158:161], v[204:207], v[70:73]
	v_mfma_f32_16x16x32_bf16 v[66:69], v[166:169], v[204:207], v[66:69]
	v_mfma_f32_16x16x32_bf16 v[118:121], v[162:165], v[178:181], v[118:121]
	v_mfma_f32_16x16x32_bf16 v[114:117], v[170:173], v[178:181], v[114:117]
	v_mfma_f32_16x16x32_bf16 v[102:105], v[162:165], v[192:195], v[102:105]
	v_mfma_f32_16x16x32_bf16 v[98:101], v[170:173], v[192:195], v[98:101]
	v_mfma_f32_16x16x32_bf16 v[86:89], v[162:165], v[200:203], v[86:89]
	v_mfma_f32_16x16x32_bf16 v[82:85], v[170:173], v[200:203], v[82:85]
	v_mfma_f32_16x16x32_bf16 v[70:73], v[162:165], v[218:221], v[70:73]
	v_mfma_f32_16x16x32_bf16 v[66:69], v[170:173], v[218:221], v[66:69]
	s_barrier
; #define PG8_STAGE(bufoff, gbase, voff) do { _Pragma("unroll") for (int _i = 0; _i < 2; ++_i) \
;         __builtin_amdgcn_global_load_lds((const unsigned*)((const char*)(gbase) + (voff)[_i]), (PG8_LAS unsigned*)(lds + (bufoff) + ldsw + _i * 8192), 16, 0, 0); } while (0)
; #define PG8_LDA(dst, b, h) do { _Pragma("unroll") for (int m = 0; m < 4; ++m) _Pragma("unroll") for (int k = 0; k < 2; ++k) dst[m][k] = *(const PG8_LAS bf16x8*)(lds + PG8_SA(b, h) + aoff + m * 2048 + k * 1024); } while (0)
; #define PG8_MMA(ai, bj, At, Bt) do { __builtin_amdgcn_s_setprio(1); _Pragma("unroll") for (int m = 0; m < 4; ++m) _Pragma("unroll") for (int n = 0; n < 2; ++n) _Pragma("unroll") for (int k = 0; k < 2; ++k) \
;         acc[ai][bj][m][n] = __builtin_amdgcn_mfma_f32_16x16x32_bf16(Bt[n][k], At[m][k], acc[ai][bj][m][n], 0, 0, 0); __builtin_amdgcn_s_setprio(0); } while (0)
; #define PG8_WAIT_V(n) asm volatile("s_waitcnt vmcnt(" #n ")" ::: "memory")
; #define PG8_WAIT_L(n) asm volatile("s_waitcnt lgkmcnt(" #n ")" ::: "memory")
; #define PG8_BAR __builtin_amdgcn_s_barrier()
; #define PG8_SCHED __builtin_amdgcn_sched_barrier(0)
; template <class Epi, class Sched, bool ALIGN_EPI = false, bool SP2 = false>
; __device__ __forceinline__ void gemm_phase(PG8_LAS unsigned char* lds, const Gemm g, const Sched& S, const Epi& E, const int wv) {
;     ...
;             PG8_LDA(At, 1, 1); PG8_STAGE(PG8_SB(1, 0), b3, voffB); PG8_STAGE(PG8_SB(1, 1), b3 + hstep, voffB); PG8_STAGE(PG8_SA(1, 0), a3, voffA);
;             PG8_WAIT_V(8); PG8_WAIT_L(0); PG8_BAR; PG8_MMA(1, 0, At, B0); PG8_MMA(1, 1, At, B1); PG8_BAR; PG8_SCHED;
;     ...
;         if constexpr (ALIGN_EPI) { if (wr == 0) PG8_BAR; }
	s_setprio 0
	s_add_i32 s28, s51, s35
	v_lshl_add_u64 v[208:209], v[208:209], 0, s[2:3]
	s_mov_b32 m0, s28
	ds_read_b128 v[174:177], v186 offset:49152
	ds_read_b128 v[178:181], v186 offset:50176
	ds_read_b128 v[188:191], v186 offset:51200
	ds_read_b128 v[192:195], v186 offset:52224
	ds_read_b128 v[196:199], v186 offset:53248
	ds_read_b128 v[200:203], v186 offset:54272
	ds_read_b128 v[204:207], v186 offset:55296
	ds_read_b128 v[218:221], v186 offset:56320
	global_load_lds_dwordx4 v[208:209], off
	s_add_i32 m0, s28, 0x2000
	s_add_u32 s26, s26, 0x40080
	v_lshl_add_u64 v[208:209], v[210:211], 0, s[2:3]
	s_addc_u32 s27, s27, 0
	s_add_i32 s28, s52, s35
	global_load_lds_dwordx4 v[208:209], off
	v_lshl_add_u64 v[208:209], s[26:27], 0, v[134:135]
	s_mov_b32 m0, s28
	s_nop 0
	global_load_lds_dwordx4 v[208:209], off
	v_lshl_add_u64 v[208:209], s[26:27], 0, v[130:131]
	s_add_i32 m0, s28, 0x2000
	s_nop 0
	global_load_lds_dwordx4 v[208:209], off
	v_lshl_add_u64 v[208:209], v[212:213], 0, s[2:3]
	s_mov_b32 m0, s44
	s_nop 0
	global_load_lds_dwordx4 v[208:209], off
	v_lshl_add_u64 v[208:209], v[214:215], 0, s[2:3]
	s_mov_b32 m0, s45
	s_nop 0
	global_load_lds_dwordx4 v[208:209], off
	s_waitcnt vmcnt(8)
	s_waitcnt lgkmcnt(0)
	s_barrier
	s_setprio 1
	s_waitcnt lgkmcnt(0)
	v_mfma_f32_16x16x32_bf16 v[62:65], v[142:145], v[174:177], v[62:65]
	v_mfma_f32_16x16x32_bf16 v[58:61], v[150:153], v[174:177], v[58:61]
	v_mfma_f32_16x16x32_bf16 v[46:49], v[142:145], v[188:191], v[46:49]
	v_mfma_f32_16x16x32_bf16 v[42:45], v[150:153], v[188:191], v[42:45]
	v_mfma_f32_16x16x32_bf16 v[30:33], v[142:145], v[196:199], v[30:33]
	v_mfma_f32_16x16x32_bf16 v[26:29], v[150:153], v[196:199], v[26:29]
	v_mfma_f32_16x16x32_bf16 v[14:17], v[142:145], v[204:207], v[14:17]
	v_mfma_f32_16x16x32_bf16 v[10:13], v[150:153], v[204:207], v[10:13]
	v_mfma_f32_16x16x32_bf16 v[62:65], v[146:149], v[178:181], v[62:65]
	v_mfma_f32_16x16x32_bf16 v[58:61], v[154:157], v[178:181], v[58:61]
	v_mfma_f32_16x16x32_bf16 v[46:49], v[146:149], v[192:195], v[46:49]
	v_mfma_f32_16x16x32_bf16 v[42:45], v[154:157], v[192:195], v[42:45]
	v_mfma_f32_16x16x32_bf16 v[30:33], v[146:149], v[200:203], v[30:33]
	v_mfma_f32_16x16x32_bf16 v[26:29], v[154:157], v[200:203], v[26:29]
	v_mfma_f32_16x16x32_bf16 v[14:17], v[146:149], v[218:221], v[14:17]
	v_mfma_f32_16x16x32_bf16 v[10:13], v[154:157], v[218:221], v[10:13]
	s_setprio 0
	s_setprio 1
	v_mfma_f32_16x16x32_bf16 v[54:57], v[158:161], v[174:177], v[54:57]
	v_mfma_f32_16x16x32_bf16 v[50:53], v[166:169], v[174:177], v[50:53]
	v_mfma_f32_16x16x32_bf16 v[38:41], v[158:161], v[188:191], v[38:41]
	v_mfma_f32_16x16x32_bf16 v[34:37], v[166:169], v[188:191], v[34:37]
	v_mfma_f32_16x16x32_bf16 v[22:25], v[158:161], v[196:199], v[22:25]
	v_mfma_f32_16x16x32_bf16 v[18:21], v[166:169], v[196:199], v[18:21]
	v_mfma_f32_16x16x32_bf16 v[6:9], v[158:161], v[204:207], v[6:9]
	v_mfma_f32_16x16x32_bf16 v[2:5], v[166:169], v[204:207], v[2:5]
	v_mfma_f32_16x16x32_bf16 v[54:57], v[162:165], v[178:181], v[54:57]
	v_mfma_f32_16x16x32_bf16 v[50:53], v[170:173], v[178:181], v[50:53]
	v_mfma_f32_16x16x32_bf16 v[38:41], v[162:165], v[192:195], v[38:41]
	v_mfma_f32_16x16x32_bf16 v[34:37], v[170:173], v[192:195], v[34:37]
	v_mfma_f32_16x16x32_bf16 v[22:25], v[162:165], v[200:203], v[22:25]
	v_mfma_f32_16x16x32_bf16 v[18:21], v[170:173], v[200:203], v[18:21]
	v_mfma_f32_16x16x32_bf16 v[6:9], v[162:165], v[218:221], v[6:9]
	v_mfma_f32_16x16x32_bf16 v[2:5], v[170:173], v[218:221], v[2:5]
	s_barrier
	s_setprio 0
	s_add_i32 s50, s50, 2
	s_add_u32 s24, s24, 0x100
	s_addc_u32 s25, s25, 0
	s_add_u32 s48, s48, 0x100
	s_addc_u32 s49, s49, 0
	s_cmp_gt_u32 s50, 13
	s_cbranch_scc0 .LBB0_134
	s_and_b64 vcc, exec, s[10:11]
	s_cbranch_vccz .LBB0_137
	s_barrier

; #define PG8_STAGE(bufoff, gbase, voff) do { _Pragma("unroll") for (int _i = 0; _i < 2; ++_i) \
;         __builtin_amdgcn_global_load_lds((const unsigned*)((const char*)(gbase) + (voff)[_i]), (PG8_LAS unsigned*)(lds + (bufoff) + ldsw + _i * 8192), 16, 0, 0); } while (0)
; #define PG8_LDA(dst, b, h) do { _Pragma("unroll") for (int m = 0; m < 4; ++m) _Pragma("unroll") for (int k = 0; k < 2; ++k) dst[m][k] = *(const PG8_LAS bf16x8*)(lds + PG8_SA(b, h) + aoff + m * 2048 + k * 1024); } while (0)
; #define PG8_LDB(dst, b, h) do { _Pragma("unroll") for (int n = 0; n < 2; ++n) _Pragma("unroll") for (int k = 0; k < 2; ++k) dst[n][k] = *(const PG8_LAS bf16x8*)(lds + PG8_SB(b, h) + boff + n * 2048 + k * 1024); } while (0)
; #define PG8_MMA(ai, bj, At, Bt) do { __builtin_amdgcn_s_setprio(1); _Pragma("unroll") for (int m = 0; m < 4; ++m) _Pragma("unroll") for (int n = 0; n < 2; ++n) _Pragma("unroll") for (int k = 0; k < 2; ++k) \
;         acc[ai][bj][m][n] = __builtin_amdgcn_mfma_f32_16x16x32_bf16(Bt[n][k], At[m][k], acc[ai][bj][m][n], 0, 0, 0); __builtin_amdgcn_s_setprio(0); } while (0)
; #define PG8_WAIT_V(n) asm volatile("s_waitcnt vmcnt(" #n ")" ::: "memory")
; #define PG8_WAIT_L(n) asm volatile("s_waitcnt lgkmcnt(" #n ")" ::: "memory")
; template <class Epi, class Sched, bool ALIGN_EPI = false, bool SP2 = false>
; __device__ __forceinline__ void gemm_phase(PG8_LAS unsigned char* lds, const Gemm g, const Sched& S, const Epi& E, const int wv) {
;     ...
;             const bool last = (t == nt - 2);
;             const char* a1 = cA + (size_t)(t + 1) * kstep;
;             const char* a2 = last ? nA : cA + (size_t)(t + 2) * kstep; const char* b2 = last ? nB : cB + (size_t)(t + 2) * kstep;
;             const char* a3 = a2 + kstep; const char* b3 = b2 + kstep;
;             if (last && has_next) S.a_ready(nxt);
;             if constexpr (SP2) {
;             PG8_LDB(B0, 0, 0); PG8_LDB(B1, 0, 1); PG8_SCHED; PG8_LDA(At, 0, 0); PG8_STAGE(PG8_SA(1, 1), a1 + hstep, voffA);
;             PG8_WAIT_V(8); PG8_WAIT_L(0); PG8_BAR; PG8_MMA(0, 0, At, B0); PG8_MMA(0, 1, At, B1); PG8_BAR; PG8_SCHED;
;             PG8_LDA(At, 0, 1); PG8_STAGE(PG8_SB(0, 0), b2, voffB); PG8_STAGE(PG8_SB(0, 1), b2 + hstep, voffB); PG8_STAGE(PG8_SA(0, 0), a2, voffA);
;             PG8_WAIT_V(8); PG8_WAIT_L(0); PG8_BAR; PG8_MMA(1, 0, At, B0); PG8_MMA(1, 1, At, B1); PG8_BAR; PG8_SCHED;
.LBB0_156:
	s_add_u32 s20, s18, 0xfffc0080
	s_addc_u32 s21, s19, -1
	s_add_i32 s45, 0, 0x10000
	s_cmp_eq_u32 s44, 12
	s_cselect_b32 s23, s11, s21
	s_cselect_b32 s22, s40, s20
	v_add_u32_e32 v152, s45, v155
	s_cselect_b32 s21, s9, s43
	s_cselect_b32 s20, s41, s42
	s_add_i32 s48, 0, 0x14000
	ds_read_b128 v[140:143], v152
	ds_read_b128 v[144:147], v152 offset:1024
	ds_read_b128 v[148:151], v152 offset:2048
	ds_read_b128 v[158:161], v152 offset:3072
	v_add_u32_e32 v152, s48, v155
	ds_read_b128 v[162:165], v152
	ds_read_b128 v[166:169], v152 offset:1024
	ds_read_b128 v[170:173], v152 offset:2048
	ds_read_b128 v[174:177], v152 offset:3072
	v_lshl_add_u64 v[152:153], s[18:19], 0, v[136:137]
	s_add_i32 m0, s17, 0xc000
	ds_read_b128 v[178:181], v157
	ds_read_b128 v[182:185], v157 offset:1024
	ds_read_b128 v[186:189], v157 offset:2048
	ds_read_b128 v[190:193], v157 offset:3072
	ds_read_b128 v[194:197], v157 offset:4096
	ds_read_b128 v[198:201], v157 offset:5120
	ds_read_b128 v[202:205], v157 offset:6144
	ds_read_b128 v[206:209], v157 offset:7168
	global_load_lds_dwordx4 v[152:153], off
	v_lshl_add_u64 v[152:153], s[18:19], 0, v[138:139]
	s_add_i32 m0, s17, 0xe000
	s_nop 0
	global_load_lds_dwordx4 v[152:153], off
	s_waitcnt vmcnt(8)
	s_waitcnt lgkmcnt(0)
	s_barrier
	s_setprio 1
	s_waitcnt lgkmcnt(0)
	v_mfma_f32_16x16x32_bf16 v[126:129], v[140:143], v[178:181], v[126:129]
	v_mfma_f32_16x16x32_bf16 v[122:125], v[148:151], v[178:181], v[122:125]
	v_mfma_f32_16x16x32_bf16 v[118:121], v[140:143], v[186:189], v[118:121]
	v_mfma_f32_16x16x32_bf16 v[114:117], v[148:151], v[186:189], v[114:117]
	v_mfma_f32_16x16x32_bf16 v[98:101], v[140:143], v[194:197], v[98:101]
	v_mfma_f32_16x16x32_bf16 v[90:93], v[148:151], v[194:197], v[90:93]
	v_mfma_f32_16x16x32_bf16 v[78:81], v[140:143], v[202:205], v[78:81]
	v_mfma_f32_16x16x32_bf16 v[74:77], v[148:151], v[202:205], v[74:77]
	v_mfma_f32_16x16x32_bf16 v[126:129], v[144:147], v[182:185], v[126:129]
	v_mfma_f32_16x16x32_bf16 v[122:125], v[158:161], v[182:185], v[122:125]
	v_mfma_f32_16x16x32_bf16 v[118:121], v[144:147], v[190:193], v[118:121]
	v_mfma_f32_16x16x32_bf16 v[114:117], v[158:161], v[190:193], v[114:117]
	v_mfma_f32_16x16x32_bf16 v[98:101], v[144:147], v[198:201], v[98:101]
	v_mfma_f32_16x16x32_bf16 v[90:93], v[158:161], v[198:201], v[90:93]
	v_mfma_f32_16x16x32_bf16 v[78:81], v[144:147], v[206:209], v[78:81]
	v_mfma_f32_16x16x32_bf16 v[74:77], v[158:161], v[206:209], v[74:77]
	s_setprio 0
	s_setprio 1
	v_mfma_f32_16x16x32_bf16 v[110:113], v[162:165], v[178:181], v[110:113]
	v_mfma_f32_16x16x32_bf16 v[106:109], v[170:173], v[178:181], v[106:109]
	v_mfma_f32_16x16x32_bf16 v[102:105], v[162:165], v[186:189], v[102:105]
	v_mfma_f32_16x16x32_bf16 v[94:97], v[170:173], v[186:189], v[94:97]
	v_mfma_f32_16x16x32_bf16 v[86:89], v[162:165], v[194:197], v[86:89]
	v_mfma_f32_16x16x32_bf16 v[82:85], v[170:173], v[194:197], v[82:85]
	v_mfma_f32_16x16x32_bf16 v[70:73], v[162:165], v[202:205], v[70:73]
	v_mfma_f32_16x16x32_bf16 v[66:69], v[170:173], v[202:205], v[66:69]
	v_mfma_f32_16x16x32_bf16 v[110:113], v[166:169], v[182:185], v[110:113]
	v_mfma_f32_16x16x32_bf16 v[106:109], v[174:177], v[182:185], v[106:109]
	v_mfma_f32_16x16x32_bf16 v[102:105], v[166:169], v[190:193], v[102:105]
	v_mfma_f32_16x16x32_bf16 v[94:97], v[174:177], v[190:193], v[94:97]
	v_mfma_f32_16x16x32_bf16 v[86:89], v[166:169], v[198:201], v[86:89]
	v_mfma_f32_16x16x32_bf16 v[82:85], v[174:177], v[198:201], v[82:85]
	v_mfma_f32_16x16x32_bf16 v[70:73], v[166:169], v[206:209], v[70:73]
	v_mfma_f32_16x16x32_bf16 v[66:69], v[174:177], v[206:209], v[66:69]
	s_barrier
	s_setprio 0
	s_add_i32 s45, s45, s24
	v_lshl_add_u64 v[152:153], s[20:21], 0, v[0:1]
	s_mov_b32 m0, s45
	ds_read_b128 v[178:181], v157 offset:16384
	ds_read_b128 v[182:185], v157 offset:17408
	ds_read_b128 v[186:189], v157 offset:18432
	ds_read_b128 v[190:193], v157 offset:19456
	ds_read_b128 v[194:197], v157 offset:20480
	ds_read_b128 v[198:201], v157 offset:21504
	ds_read_b128 v[202:205], v157 offset:22528
	ds_read_b128 v[206:209], v157 offset:23552
	global_load_lds_dwordx4 v[152:153], off
	s_add_i32 m0, s45, 0x2000
	s_add_u32 s46, s20, 0x40000
	v_lshl_add_u64 v[210:211], s[20:21], 0, v[130:131]
	s_addc_u32 s47, s21, 0
	s_add_i32 s45, s48, s24
	global_load_lds_dwordx4 v[210:211], off
	v_lshl_add_u64 v[212:213], s[46:47], 0, v[0:1]
	s_mov_b32 m0, s45
	v_lshl_add_u64 v[214:215], s[22:23], 0, v[132:133]
	global_load_lds_dwordx4 v[212:213], off
	v_lshl_add_u64 v[212:213], s[46:47], 0, v[130:131]
	s_add_i32 m0, s45, 0x2000
	s_nop 0
	global_load_lds_dwordx4 v[212:213], off
	v_lshl_add_u64 v[212:213], s[22:23], 0, v[134:135]
	s_mov_b32 m0, s17
	s_nop 0
	global_load_lds_dwordx4 v[212:213], off
	s_mov_b32 m0, s26
	s_nop 0
	global_load_lds_dwordx4 v[214:215], off
	s_waitcnt vmcnt(8)
	s_waitcnt lgkmcnt(0)
	s_barrier
; #define PG8_STAGE(bufoff, gbase, voff) do { _Pragma("unroll") for (int _i = 0; _i < 2; ++_i) \
;         __builtin_amdgcn_global_load_lds((const unsigned*)((const char*)(gbase) + (voff)[_i]), (PG8_LAS unsigned*)(lds + (bufoff) + ldsw + _i * 8192), 16, 0, 0); } while (0)
; #define PG8_LDA(dst, b, h) do { _Pragma("unroll") for (int m = 0; m < 4; ++m) _Pragma("unroll") for (int k = 0; k < 2; ++k) dst[m][k] = *(const PG8_LAS bf16x8*)(lds + PG8_SA(b, h) + aoff + m * 2048 + k * 1024); } while (0)
; #define PG8_LDB(dst, b, h) do { _Pragma("unroll") for (int n = 0; n < 2; ++n) _Pragma("unroll") for (int k = 0; k < 2; ++k) dst[n][k] = *(const PG8_LAS bf16x8*)(lds + PG8_SB(b, h) + boff + n * 2048 + k * 1024); } while (0)
; #define PG8_MMA(ai, bj, At, Bt) do { __builtin_amdgcn_s_setprio(1); _Pragma("unroll") for (int m = 0; m < 4; ++m) _Pragma("unroll") for (int n = 0; n < 2; ++n) _Pragma("unroll") for (int k = 0; k < 2; ++k) \
;         acc[ai][bj][m][n] = __builtin_amdgcn_mfma_f32_16x16x32_bf16(Bt[n][k], At[m][k], acc[ai][bj][m][n], 0, 0, 0); __builtin_amdgcn_s_setprio(0); } while (0)
; #define PG8_WAIT_V(n) asm volatile("s_waitcnt vmcnt(" #n ")" ::: "memory")
; #define PG8_WAIT_L(n) asm volatile("s_waitcnt lgkmcnt(" #n ")" ::: "memory")
; #define PG8_BAR __builtin_amdgcn_s_barrier()
; #define PG8_SCHED __builtin_amdgcn_sched_barrier(0)
; template <class Epi, class Sched, bool ALIGN_EPI = false, bool SP2 = false>
; __device__ __forceinline__ void gemm_phase(PG8_LAS unsigned char* lds, const Gemm g, const Sched& S, const Epi& E, const int wv) {
;     ...
;             PG8_WAIT_V(8); PG8_WAIT_L(0); PG8_BAR; PG8_MMA(1, 0, At, B0); PG8_MMA(1, 1, At, B1); PG8_BAR; PG8_SCHED;
;             PG8_LDB(B0, 1, 0); PG8_LDB(B1, 1, 1); PG8_SCHED; PG8_LDA(At, 1, 0); PG8_STAGE(PG8_SA(0, 1), a2 + hstep, voffA);
;             PG8_WAIT_V(8); PG8_WAIT_L(0); PG8_BAR; PG8_MMA(0, 0, At, B0); PG8_MMA(0, 1, At, B1); PG8_BAR; PG8_SCHED;
	s_setprio 1
	s_waitcnt lgkmcnt(0)
	v_mfma_f32_16x16x32_bf16 v[62:65], v[140:143], v[178:181], v[62:65]
	v_mfma_f32_16x16x32_bf16 v[58:61], v[148:151], v[178:181], v[58:61]
	v_mfma_f32_16x16x32_bf16 v[46:49], v[140:143], v[186:189], v[46:49]
	v_mfma_f32_16x16x32_bf16 v[42:45], v[148:151], v[186:189], v[42:45]
	v_mfma_f32_16x16x32_bf16 v[30:33], v[140:143], v[194:197], v[30:33]
	v_mfma_f32_16x16x32_bf16 v[26:29], v[148:151], v[194:197], v[26:29]
	v_mfma_f32_16x16x32_bf16 v[14:17], v[140:143], v[202:205], v[14:17]
	v_mfma_f32_16x16x32_bf16 v[10:13], v[148:151], v[202:205], v[10:13]
	v_mfma_f32_16x16x32_bf16 v[62:65], v[144:147], v[182:185], v[62:65]
	v_mfma_f32_16x16x32_bf16 v[58:61], v[158:161], v[182:185], v[58:61]
	v_mfma_f32_16x16x32_bf16 v[46:49], v[144:147], v[190:193], v[46:49]
	v_mfma_f32_16x16x32_bf16 v[42:45], v[158:161], v[190:193], v[42:45]
	v_mfma_f32_16x16x32_bf16 v[30:33], v[144:147], v[198:201], v[30:33]
	v_mfma_f32_16x16x32_bf16 v[26:29], v[158:161], v[198:201], v[26:29]
	v_mfma_f32_16x16x32_bf16 v[14:17], v[144:147], v[206:209], v[14:17]
	v_mfma_f32_16x16x32_bf16 v[10:13], v[158:161], v[206:209], v[10:13]
	s_setprio 0
	s_setprio 1
	v_mfma_f32_16x16x32_bf16 v[54:57], v[162:165], v[178:181], v[54:57]
	v_mfma_f32_16x16x32_bf16 v[50:53], v[170:173], v[178:181], v[50:53]
	v_mfma_f32_16x16x32_bf16 v[38:41], v[162:165], v[186:189], v[38:41]
	v_mfma_f32_16x16x32_bf16 v[34:37], v[170:173], v[186:189], v[34:37]
	v_mfma_f32_16x16x32_bf16 v[22:25], v[162:165], v[194:197], v[22:25]
	v_mfma_f32_16x16x32_bf16 v[18:21], v[170:173], v[194:197], v[18:21]
	v_mfma_f32_16x16x32_bf16 v[6:9], v[162:165], v[202:205], v[6:9]
	v_mfma_f32_16x16x32_bf16 v[2:5], v[170:173], v[202:205], v[2:5]
	v_mfma_f32_16x16x32_bf16 v[54:57], v[166:169], v[182:185], v[54:57]
	v_mfma_f32_16x16x32_bf16 v[50:53], v[174:177], v[182:185], v[50:53]
	v_mfma_f32_16x16x32_bf16 v[38:41], v[166:169], v[190:193], v[38:41]
	v_mfma_f32_16x16x32_bf16 v[34:37], v[174:177], v[190:193], v[34:37]
	v_mfma_f32_16x16x32_bf16 v[22:25], v[166:169], v[198:201], v[22:25]
	v_mfma_f32_16x16x32_bf16 v[18:21], v[174:177], v[198:201], v[18:21]
	v_mfma_f32_16x16x32_bf16 v[6:9], v[166:169], v[206:209], v[6:9]
	v_mfma_f32_16x16x32_bf16 v[2:5], v[174:177], v[206:209], v[2:5]
	s_barrier
	s_setprio 0
	s_add_i32 s45, 0, 0x18000
	s_add_i32 s46, 0, 0x1c000
	v_add_u32_e32 v158, s45, v155
	v_add_u32_e32 v174, s46, v155
	ds_read_b128 v[140:143], v158
	ds_read_b128 v[144:147], v158 offset:1024
	ds_read_b128 v[148:151], v158 offset:2048
	ds_read_b128 v[158:161], v158 offset:3072
	ds_read_b128 v[162:165], v174
	ds_read_b128 v[166:169], v174 offset:1024
	ds_read_b128 v[170:173], v174 offset:2048
	ds_read_b128 v[174:177], v174 offset:3072
	s_add_u32 s22, s22, 0x40000
	s_addc_u32 s23, s23, 0
	s_mov_b32 m0, s27
	v_lshl_add_u64 v[216:217], s[22:23], 0, v[134:135]
	ds_read_b128 v[178:181], v157 offset:32768
	ds_read_b128 v[182:185], v157 offset:33792
	ds_read_b128 v[186:189], v157 offset:34816
	ds_read_b128 v[190:193], v157 offset:35840
	ds_read_b128 v[194:197], v157 offset:36864
	ds_read_b128 v[198:201], v157 offset:37888
	ds_read_b128 v[202:205], v157 offset:38912
	ds_read_b128 v[206:209], v157 offset:39936
	global_load_lds_dwordx4 v[216:217], off
	v_lshl_add_u64 v[216:217], s[22:23], 0, v[132:133]
	s_mov_b32 m0, s28
	s_nop 0
	global_load_lds_dwordx4 v[216:217], off
	s_waitcnt vmcnt(8)
	s_waitcnt lgkmcnt(0)
	s_barrier
	s_setprio 1
	s_waitcnt lgkmcnt(0)
	v_mfma_f32_16x16x32_bf16 v[126:129], v[140:143], v[178:181], v[126:129]
	v_mfma_f32_16x16x32_bf16 v[122:125], v[148:151], v[178:181], v[122:125]
	v_mfma_f32_16x16x32_bf16 v[118:121], v[140:143], v[186:189], v[118:121]
	v_mfma_f32_16x16x32_bf16 v[114:117], v[148:151], v[186:189], v[114:117]
	v_mfma_f32_16x16x32_bf16 v[98:101], v[140:143], v[194:197], v[98:101]
	v_mfma_f32_16x16x32_bf16 v[90:93], v[148:151], v[194:197], v[90:93]
	v_mfma_f32_16x16x32_bf16 v[78:81], v[140:143], v[202:205], v[78:81]
	v_mfma_f32_16x16x32_bf16 v[74:77], v[148:151], v[202:205], v[74:77]
	v_mfma_f32_16x16x32_bf16 v[126:129], v[144:147], v[182:185], v[126:129]
	v_mfma_f32_16x16x32_bf16 v[122:125], v[158:161], v[182:185], v[122:125]
	v_mfma_f32_16x16x32_bf16 v[118:121], v[144:147], v[190:193], v[118:121]
	v_mfma_f32_16x16x32_bf16 v[114:117], v[158:161], v[190:193], v[114:117]
	v_mfma_f32_16x16x32_bf16 v[98:101], v[144:147], v[198:201], v[98:101]
	v_mfma_f32_16x16x32_bf16 v[90:93], v[158:161], v[198:201], v[90:93]
	v_mfma_f32_16x16x32_bf16 v[78:81], v[144:147], v[206:209], v[78:81]
	v_mfma_f32_16x16x32_bf16 v[74:77], v[158:161], v[206:209], v[74:77]
	s_setprio 0
	s_setprio 1
	v_mfma_f32_16x16x32_bf16 v[110:113], v[162:165], v[178:181], v[110:113]
	v_mfma_f32_16x16x32_bf16 v[106:109], v[170:173], v[178:181], v[106:109]
	v_mfma_f32_16x16x32_bf16 v[102:105], v[162:165], v[186:189], v[102:105]
	v_mfma_f32_16x16x32_bf16 v[94:97], v[170:173], v[186:189], v[94:97]
	v_mfma_f32_16x16x32_bf16 v[86:89], v[162:165], v[194:197], v[86:89]
	v_mfma_f32_16x16x32_bf16 v[82:85], v[170:173], v[194:197], v[82:85]
	v_mfma_f32_16x16x32_bf16 v[70:73], v[162:165], v[202:205], v[70:73]
	v_mfma_f32_16x16x32_bf16 v[66:69], v[170:173], v[202:205], v[66:69]
	v_mfma_f32_16x16x32_bf16 v[110:113], v[166:169], v[182:185], v[110:113]
	v_mfma_f32_16x16x32_bf16 v[106:109], v[174:177], v[182:185], v[106:109]
	v_mfma_f32_16x16x32_bf16 v[102:105], v[166:169], v[190:193], v[102:105]
	v_mfma_f32_16x16x32_bf16 v[94:97], v[174:177], v[190:193], v[94:97]
	v_mfma_f32_16x16x32_bf16 v[86:89], v[166:169], v[198:201], v[86:89]
	v_mfma_f32_16x16x32_bf16 v[82:85], v[174:177], v[198:201], v[82:85]
	v_mfma_f32_16x16x32_bf16 v[70:73], v[166:169], v[206:209], v[70:73]
	v_mfma_f32_16x16x32_bf16 v[66:69], v[174:177], v[206:209], v[66:69]
	s_barrier
; #define PG8_STAGE(bufoff, gbase, voff) do { _Pragma("unroll") for (int _i = 0; _i < 2; ++_i) \
;         __builtin_amdgcn_global_load_lds((const unsigned*)((const char*)(gbase) + (voff)[_i]), (PG8_LAS unsigned*)(lds + (bufoff) + ldsw + _i * 8192), 16, 0, 0); } while (0)
; #define PG8_LDA(dst, b, h) do { _Pragma("unroll") for (int m = 0; m < 4; ++m) _Pragma("unroll") for (int k = 0; k < 2; ++k) dst[m][k] = *(const PG8_LAS bf16x8*)(lds + PG8_SA(b, h) + aoff + m * 2048 + k * 1024); } while (0)
; #define PG8_MMA(ai, bj, At, Bt) do { __builtin_amdgcn_s_setprio(1); _Pragma("unroll") for (int m = 0; m < 4; ++m) _Pragma("unroll") for (int n = 0; n < 2; ++n) _Pragma("unroll") for (int k = 0; k < 2; ++k) \
;         acc[ai][bj][m][n] = __builtin_amdgcn_mfma_f32_16x16x32_bf16(Bt[n][k], At[m][k], acc[ai][bj][m][n], 0, 0, 0); __builtin_amdgcn_s_setprio(0); } while (0)
; #define PG8_WAIT_V(n) asm volatile("s_waitcnt vmcnt(" #n ")" ::: "memory")
; #define PG8_WAIT_L(n) asm volatile("s_waitcnt lgkmcnt(" #n ")" ::: "memory")
; #define PG8_BAR __builtin_amdgcn_s_barrier()
; #define PG8_SCHED __builtin_amdgcn_sched_barrier(0)
; template <class Epi, class Sched, bool ALIGN_EPI = false, bool SP2 = false>
; __device__ __forceinline__ void gemm_phase(PG8_LAS unsigned char* lds, const Gemm g, const Sched& S, const Epi& E, const int wv) {
;     ...
;             PG8_LDA(At, 1, 1); PG8_STAGE(PG8_SB(1, 0), b3, voffB); PG8_STAGE(PG8_SB(1, 1), b3 + hstep, voffB); PG8_STAGE(PG8_SA(1, 0), a3, voffA);
;             PG8_WAIT_V(8); PG8_WAIT_L(0); PG8_BAR; PG8_MMA(1, 0, At, B0); PG8_MMA(1, 1, At, B1); PG8_BAR; PG8_SCHED;
;     ...
;         if constexpr (ALIGN_EPI) { if (wr == 0) PG8_BAR; }
	s_setprio 0
	s_add_i32 s22, s45, s24
	v_lshl_add_u64 v[152:153], v[152:153], 0, s[2:3]
	s_mov_b32 m0, s22
	ds_read_b128 v[178:181], v157 offset:49152
	ds_read_b128 v[182:185], v157 offset:50176
	ds_read_b128 v[186:189], v157 offset:51200
	ds_read_b128 v[190:193], v157 offset:52224
	ds_read_b128 v[194:197], v157 offset:53248
	ds_read_b128 v[198:201], v157 offset:54272
	ds_read_b128 v[202:205], v157 offset:55296
	ds_read_b128 v[206:209], v157 offset:56320
	global_load_lds_dwordx4 v[152:153], off
	s_add_i32 m0, s22, 0x2000
	s_add_u32 s20, s20, 0x40080
	v_lshl_add_u64 v[152:153], v[210:211], 0, s[2:3]
	s_addc_u32 s21, s21, 0
	s_add_i32 s22, s46, s24
	global_load_lds_dwordx4 v[152:153], off
	v_lshl_add_u64 v[152:153], s[20:21], 0, v[0:1]
	s_mov_b32 m0, s22
	s_nop 0
	global_load_lds_dwordx4 v[152:153], off
	v_lshl_add_u64 v[152:153], s[20:21], 0, v[130:131]
	s_add_i32 m0, s22, 0x2000
	s_nop 0
	global_load_lds_dwordx4 v[152:153], off
	v_lshl_add_u64 v[152:153], v[212:213], 0, s[2:3]
	s_mov_b32 m0, s33
	s_nop 0
	global_load_lds_dwordx4 v[152:153], off
	v_lshl_add_u64 v[152:153], v[214:215], 0, s[2:3]
	s_mov_b32 m0, s35
	s_nop 0
	global_load_lds_dwordx4 v[152:153], off
	s_waitcnt vmcnt(8)
	s_waitcnt lgkmcnt(0)
	s_barrier
	s_setprio 1
	s_waitcnt lgkmcnt(0)
	v_mfma_f32_16x16x32_bf16 v[62:65], v[140:143], v[178:181], v[62:65]
	v_mfma_f32_16x16x32_bf16 v[58:61], v[148:151], v[178:181], v[58:61]
	v_mfma_f32_16x16x32_bf16 v[46:49], v[140:143], v[186:189], v[46:49]
	v_mfma_f32_16x16x32_bf16 v[42:45], v[148:151], v[186:189], v[42:45]
	v_mfma_f32_16x16x32_bf16 v[30:33], v[140:143], v[194:197], v[30:33]
	v_mfma_f32_16x16x32_bf16 v[26:29], v[148:151], v[194:197], v[26:29]
	v_mfma_f32_16x16x32_bf16 v[14:17], v[140:143], v[202:205], v[14:17]
	v_mfma_f32_16x16x32_bf16 v[10:13], v[148:151], v[202:205], v[10:13]
	v_mfma_f32_16x16x32_bf16 v[62:65], v[144:147], v[182:185], v[62:65]
	v_mfma_f32_16x16x32_bf16 v[58:61], v[158:161], v[182:185], v[58:61]
	v_mfma_f32_16x16x32_bf16 v[46:49], v[144:147], v[190:193], v[46:49]
	v_mfma_f32_16x16x32_bf16 v[42:45], v[158:161], v[190:193], v[42:45]
	v_mfma_f32_16x16x32_bf16 v[30:33], v[144:147], v[198:201], v[30:33]
	v_mfma_f32_16x16x32_bf16 v[26:29], v[158:161], v[198:201], v[26:29]
	v_mfma_f32_16x16x32_bf16 v[14:17], v[144:147], v[206:209], v[14:17]
	v_mfma_f32_16x16x32_bf16 v[10:13], v[158:161], v[206:209], v[10:13]
	s_setprio 0
	s_setprio 1
	v_mfma_f32_16x16x32_bf16 v[54:57], v[162:165], v[178:181], v[54:57]
	v_mfma_f32_16x16x32_bf16 v[50:53], v[170:173], v[178:181], v[50:53]
	v_mfma_f32_16x16x32_bf16 v[38:41], v[162:165], v[186:189], v[38:41]
	v_mfma_f32_16x16x32_bf16 v[34:37], v[170:173], v[186:189], v[34:37]
	v_mfma_f32_16x16x32_bf16 v[22:25], v[162:165], v[194:197], v[22:25]
	v_mfma_f32_16x16x32_bf16 v[18:21], v[170:173], v[194:197], v[18:21]
	v_mfma_f32_16x16x32_bf16 v[6:9], v[162:165], v[202:205], v[6:9]
	v_mfma_f32_16x16x32_bf16 v[2:5], v[170:173], v[202:205], v[2:5]
	v_mfma_f32_16x16x32_bf16 v[54:57], v[166:169], v[182:185], v[54:57]
	v_mfma_f32_16x16x32_bf16 v[50:53], v[174:177], v[182:185], v[50:53]
	v_mfma_f32_16x16x32_bf16 v[38:41], v[166:169], v[190:193], v[38:41]
	v_mfma_f32_16x16x32_bf16 v[34:37], v[174:177], v[190:193], v[34:37]
	v_mfma_f32_16x16x32_bf16 v[22:25], v[166:169], v[198:201], v[22:25]
	v_mfma_f32_16x16x32_bf16 v[18:21], v[174:177], v[198:201], v[18:21]
	v_mfma_f32_16x16x32_bf16 v[6:9], v[166:169], v[206:209], v[6:9]
	v_mfma_f32_16x16x32_bf16 v[2:5], v[174:177], v[206:209], v[2:5]
	s_barrier
	s_setprio 0
	s_add_i32 s44, s44, 2
	s_add_u32 s18, s18, 0x100
	s_addc_u32 s19, s19, 0
	s_add_u32 s42, s42, 0x100
	s_addc_u32 s43, s43, 0
	s_cmp_gt_u32 s44, 13
	s_cbranch_scc0 .LBB0_156
	s_and_b64 vcc, exec, s[6:7]
	s_cbranch_vccz .LBB0_159
	s_barrier

; #define PG8_STAGE(bufoff, gbase, voff) do { _Pragma("unroll") for (int _i = 0; _i < 2; ++_i) \
;         __builtin_amdgcn_global_load_lds((const unsigned*)((const char*)(gbase) + (voff)[_i]), (PG8_LAS unsigned*)(lds + (bufoff) + ldsw + _i * 8192), 16, 0, 0); } while (0)
; #define PG8_LDA(dst, b, h) do { _Pragma("unroll") for (int m = 0; m < 4; ++m) _Pragma("unroll") for (int k = 0; k < 2; ++k) dst[m][k] = *(const PG8_LAS bf16x8*)(lds + PG8_SA(b, h) + aoff + m * 2048 + k * 1024); } while (0)
; #define PG8_LDB(dst, b, h) do { _Pragma("unroll") for (int n = 0; n < 2; ++n) _Pragma("unroll") for (int k = 0; k < 2; ++k) dst[n][k] = *(const PG8_LAS bf16x8*)(lds + PG8_SB(b, h) + boff + n * 2048 + k * 1024); } while (0)
; #define PG8_MMA(ai, bj, At, Bt) do { __builtin_amdgcn_s_setprio(1); _Pragma("unroll") for (int m = 0; m < 4; ++m) _Pragma("unroll") for (int n = 0; n < 2; ++n) _Pragma("unroll") for (int k = 0; k < 2; ++k) \
;         acc[ai][bj][m][n] = __builtin_amdgcn_mfma_f32_16x16x32_bf16(Bt[n][k], At[m][k], acc[ai][bj][m][n], 0, 0, 0); __builtin_amdgcn_s_setprio(0); } while (0)
; #define PG8_WAIT_V(n) asm volatile("s_waitcnt vmcnt(" #n ")" ::: "memory")
; #define PG8_WAIT_L(n) asm volatile("s_waitcnt lgkmcnt(" #n ")" ::: "memory")
; template <class Epi, class Sched, bool ALIGN_EPI = false, bool SP2 = false>
; __device__ __forceinline__ void gemm_phase(PG8_LAS unsigned char* lds, const Gemm g, const Sched& S, const Epi& E, const int wv) {
;     ...
;             const bool last = (t == nt - 2);
;             const char* a1 = cA + (size_t)(t + 1) * kstep;
;             const char* a2 = last ? nA : cA + (size_t)(t + 2) * kstep; const char* b2 = last ? nB : cB + (size_t)(t + 2) * kstep;
;             const char* a3 = a2 + kstep; const char* b3 = b2 + kstep;
;             if (last && has_next) S.a_ready(nxt);
;             if constexpr (SP2) {
;             PG8_LDB(B0, 0, 0); PG8_LDB(B1, 0, 1); PG8_SCHED; PG8_LDA(At, 0, 0); PG8_STAGE(PG8_SA(1, 1), a1 + hstep, voffA);
;             PG8_WAIT_V(8); PG8_WAIT_L(0); PG8_BAR; PG8_MMA(0, 0, At, B0); PG8_MMA(0, 1, At, B1); PG8_BAR; PG8_SCHED;
;             PG8_LDA(At, 0, 1); PG8_STAGE(PG8_SB(0, 0), b2, voffB); PG8_STAGE(PG8_SB(0, 1), b2 + hstep, voffB); PG8_STAGE(PG8_SA(0, 0), a2, voffA);
;             PG8_WAIT_V(8); PG8_WAIT_L(0); PG8_BAR; PG8_MMA(1, 0, At, B0); PG8_MMA(1, 1, At, B1); PG8_BAR; PG8_SCHED;
.LBB0_350:
	s_add_u32 s24, s22, 0xfffc0080
	s_addc_u32 s25, s23, -1
	s_add_i32 s48, 0, 0x10000
	s_cmp_eq_u32 s47, 12
	s_cselect_b32 s27, s13, s25
	s_cselect_b32 s26, s19, s24
	s_cselect_b32 s25, s11, s46
	s_cselect_b32 s24, s33, s45
	s_add_i32 s50, 0, 0x14000
	v_add_u32_e32 v126, s48, v183
	v_add_u32_e32 v168, s50, v183
	ds_read_b128 v[114:117], v126
	ds_read_b128 v[118:121], v126 offset:1024
	ds_read_b128 v[122:125], v126 offset:2048
	ds_read_b128 v[126:129], v126 offset:3072
	ds_read_b128 v[130:133], v168
	ds_read_b128 v[134:137], v168 offset:1024
	ds_read_b128 v[164:167], v168 offset:2048
	ds_read_b128 v[168:171], v168 offset:3072
	v_lshl_add_u64 v[180:181], s[22:23], 0, v[160:161]
	s_add_i32 m0, s21, 0xc000
	ds_read_b128 v[172:175], v185
	ds_read_b128 v[176:179], v185 offset:1024
	ds_read_b128 v[186:189], v185 offset:2048
	ds_read_b128 v[190:193], v185 offset:3072
	ds_read_b128 v[194:197], v185 offset:4096
	ds_read_b128 v[198:201], v185 offset:5120
	ds_read_b128 v[202:205], v185 offset:6144
	ds_read_b128 v[206:209], v185 offset:7168
	global_load_lds_dwordx4 v[180:181], off
	v_lshl_add_u64 v[180:181], s[22:23], 0, v[162:163]
	s_add_i32 m0, s21, 0xe000
	s_nop 0
	global_load_lds_dwordx4 v[180:181], off
	s_waitcnt vmcnt(8)
	s_waitcnt lgkmcnt(0)
	s_barrier
	s_setprio 1
	s_waitcnt lgkmcnt(0)
	v_mfma_f32_16x16x32_bf16 v[150:153], v[114:117], v[172:175], v[150:153]
	v_mfma_f32_16x16x32_bf16 v[146:149], v[122:125], v[172:175], v[146:149]
	v_mfma_f32_16x16x32_bf16 v[110:113], v[114:117], v[186:189], v[110:113]
	v_mfma_f32_16x16x32_bf16 v[106:109], v[122:125], v[186:189], v[106:109]
	v_mfma_f32_16x16x32_bf16 v[94:97], v[114:117], v[194:197], v[94:97]
	v_mfma_f32_16x16x32_bf16 v[90:93], v[122:125], v[194:197], v[90:93]
	v_mfma_f32_16x16x32_bf16 v[78:81], v[114:117], v[202:205], v[78:81]
	v_mfma_f32_16x16x32_bf16 v[74:77], v[122:125], v[202:205], v[74:77]
	v_mfma_f32_16x16x32_bf16 v[150:153], v[118:121], v[176:179], v[150:153]
	v_mfma_f32_16x16x32_bf16 v[146:149], v[126:129], v[176:179], v[146:149]
	v_mfma_f32_16x16x32_bf16 v[110:113], v[118:121], v[190:193], v[110:113]
	v_mfma_f32_16x16x32_bf16 v[106:109], v[126:129], v[190:193], v[106:109]
	v_mfma_f32_16x16x32_bf16 v[94:97], v[118:121], v[198:201], v[94:97]
	v_mfma_f32_16x16x32_bf16 v[90:93], v[126:129], v[198:201], v[90:93]
	v_mfma_f32_16x16x32_bf16 v[78:81], v[118:121], v[206:209], v[78:81]
	v_mfma_f32_16x16x32_bf16 v[74:77], v[126:129], v[206:209], v[74:77]
	s_setprio 0
	s_setprio 1
	v_mfma_f32_16x16x32_bf16 v[142:145], v[130:133], v[172:175], v[142:145]
	v_mfma_f32_16x16x32_bf16 v[138:141], v[164:167], v[172:175], v[138:141]
	v_mfma_f32_16x16x32_bf16 v[102:105], v[130:133], v[186:189], v[102:105]
	v_mfma_f32_16x16x32_bf16 v[98:101], v[164:167], v[186:189], v[98:101]
	v_mfma_f32_16x16x32_bf16 v[86:89], v[130:133], v[194:197], v[86:89]
	v_mfma_f32_16x16x32_bf16 v[82:85], v[164:167], v[194:197], v[82:85]
	v_mfma_f32_16x16x32_bf16 v[70:73], v[130:133], v[202:205], v[70:73]
	v_mfma_f32_16x16x32_bf16 v[66:69], v[164:167], v[202:205], v[66:69]
	v_mfma_f32_16x16x32_bf16 v[142:145], v[134:137], v[176:179], v[142:145]
	v_mfma_f32_16x16x32_bf16 v[138:141], v[168:171], v[176:179], v[138:141]
	v_mfma_f32_16x16x32_bf16 v[102:105], v[134:137], v[190:193], v[102:105]
	v_mfma_f32_16x16x32_bf16 v[98:101], v[168:171], v[190:193], v[98:101]
	v_mfma_f32_16x16x32_bf16 v[86:89], v[134:137], v[198:201], v[86:89]
	v_mfma_f32_16x16x32_bf16 v[82:85], v[168:171], v[198:201], v[82:85]
	v_mfma_f32_16x16x32_bf16 v[70:73], v[134:137], v[206:209], v[70:73]
	v_mfma_f32_16x16x32_bf16 v[66:69], v[168:171], v[206:209], v[66:69]
	s_barrier
	s_setprio 0
	s_add_i32 s48, s48, s36
	v_lshl_add_u64 v[180:181], s[24:25], 0, v[0:1]
	s_mov_b32 m0, s48
	ds_read_b128 v[172:175], v185 offset:16384
	ds_read_b128 v[176:179], v185 offset:17408
	ds_read_b128 v[186:189], v185 offset:18432
	ds_read_b128 v[190:193], v185 offset:19456
	ds_read_b128 v[194:197], v185 offset:20480
	ds_read_b128 v[198:201], v185 offset:21504
	ds_read_b128 v[202:205], v185 offset:22528
	ds_read_b128 v[206:209], v185 offset:23552
	global_load_lds_dwordx4 v[180:181], off
	s_add_i32 m0, s48, 0x2000
	s_add_u32 s48, s24, 0x40000
	v_lshl_add_u64 v[210:211], s[24:25], 0, v[158:159]
	s_addc_u32 s49, s25, 0
	s_add_i32 s50, s50, s36
	global_load_lds_dwordx4 v[210:211], off
	v_lshl_add_u64 v[212:213], s[48:49], 0, v[0:1]
	s_mov_b32 m0, s50
	v_lshl_add_u64 v[214:215], s[26:27], 0, v[156:157]
	global_load_lds_dwordx4 v[212:213], off
	v_lshl_add_u64 v[212:213], s[48:49], 0, v[158:159]
	s_add_i32 m0, s50, 0x2000
	s_nop 0
	global_load_lds_dwordx4 v[212:213], off
	v_lshl_add_u64 v[212:213], s[26:27], 0, v[154:155]
	s_mov_b32 m0, s21
	s_nop 0
	global_load_lds_dwordx4 v[212:213], off
	s_mov_b32 m0, s37
	s_nop 0
	global_load_lds_dwordx4 v[214:215], off
	s_waitcnt vmcnt(8)
	s_waitcnt lgkmcnt(0)
	s_barrier
; #define PG8_STAGE(bufoff, gbase, voff) do { _Pragma("unroll") for (int _i = 0; _i < 2; ++_i) \
;         __builtin_amdgcn_global_load_lds((const unsigned*)((const char*)(gbase) + (voff)[_i]), (PG8_LAS unsigned*)(lds + (bufoff) + ldsw + _i * 8192), 16, 0, 0); } while (0)
; #define PG8_LDA(dst, b, h) do { _Pragma("unroll") for (int m = 0; m < 4; ++m) _Pragma("unroll") for (int k = 0; k < 2; ++k) dst[m][k] = *(const PG8_LAS bf16x8*)(lds + PG8_SA(b, h) + aoff + m * 2048 + k * 1024); } while (0)
; #define PG8_LDB(dst, b, h) do { _Pragma("unroll") for (int n = 0; n < 2; ++n) _Pragma("unroll") for (int k = 0; k < 2; ++k) dst[n][k] = *(const PG8_LAS bf16x8*)(lds + PG8_SB(b, h) + boff + n * 2048 + k * 1024); } while (0)
; #define PG8_MMA(ai, bj, At, Bt) do { __builtin_amdgcn_s_setprio(1); _Pragma("unroll") for (int m = 0; m < 4; ++m) _Pragma("unroll") for (int n = 0; n < 2; ++n) _Pragma("unroll") for (int k = 0; k < 2; ++k) \
;         acc[ai][bj][m][n] = __builtin_amdgcn_mfma_f32_16x16x32_bf16(Bt[n][k], At[m][k], acc[ai][bj][m][n], 0, 0, 0); __builtin_amdgcn_s_setprio(0); } while (0)
; #define PG8_WAIT_V(n) asm volatile("s_waitcnt vmcnt(" #n ")" ::: "memory")
; #define PG8_WAIT_L(n) asm volatile("s_waitcnt lgkmcnt(" #n ")" ::: "memory")
; #define PG8_BAR __builtin_amdgcn_s_barrier()
; #define PG8_SCHED __builtin_amdgcn_sched_barrier(0)
; template <class Epi, class Sched, bool ALIGN_EPI = false, bool SP2 = false>
; __device__ __forceinline__ void gemm_phase(PG8_LAS unsigned char* lds, const Gemm g, const Sched& S, const Epi& E, const int wv) {
;     ...
;             PG8_WAIT_V(8); PG8_WAIT_L(0); PG8_BAR; PG8_MMA(1, 0, At, B0); PG8_MMA(1, 1, At, B1); PG8_BAR; PG8_SCHED;
;             PG8_LDB(B0, 1, 0); PG8_LDB(B1, 1, 1); PG8_SCHED; PG8_LDA(At, 1, 0); PG8_STAGE(PG8_SA(0, 1), a2 + hstep, voffA);
;             PG8_WAIT_V(8); PG8_WAIT_L(0); PG8_BAR; PG8_MMA(0, 0, At, B0); PG8_MMA(0, 1, At, B1); PG8_BAR; PG8_SCHED;
	s_setprio 1
	s_waitcnt lgkmcnt(0)
	v_mfma_f32_16x16x32_bf16 v[62:65], v[114:117], v[172:175], v[62:65]
	v_mfma_f32_16x16x32_bf16 v[58:61], v[122:125], v[172:175], v[58:61]
	v_mfma_f32_16x16x32_bf16 v[46:49], v[114:117], v[186:189], v[46:49]
	v_mfma_f32_16x16x32_bf16 v[42:45], v[122:125], v[186:189], v[42:45]
	v_mfma_f32_16x16x32_bf16 v[30:33], v[114:117], v[194:197], v[30:33]
	v_mfma_f32_16x16x32_bf16 v[26:29], v[122:125], v[194:197], v[26:29]
	v_mfma_f32_16x16x32_bf16 v[14:17], v[114:117], v[202:205], v[14:17]
	v_mfma_f32_16x16x32_bf16 v[10:13], v[122:125], v[202:205], v[10:13]
	v_mfma_f32_16x16x32_bf16 v[62:65], v[118:121], v[176:179], v[62:65]
	v_mfma_f32_16x16x32_bf16 v[58:61], v[126:129], v[176:179], v[58:61]
	v_mfma_f32_16x16x32_bf16 v[46:49], v[118:121], v[190:193], v[46:49]
	v_mfma_f32_16x16x32_bf16 v[42:45], v[126:129], v[190:193], v[42:45]
	v_mfma_f32_16x16x32_bf16 v[30:33], v[118:121], v[198:201], v[30:33]
	v_mfma_f32_16x16x32_bf16 v[26:29], v[126:129], v[198:201], v[26:29]
	v_mfma_f32_16x16x32_bf16 v[14:17], v[118:121], v[206:209], v[14:17]
	v_mfma_f32_16x16x32_bf16 v[10:13], v[126:129], v[206:209], v[10:13]
	s_setprio 0
	s_setprio 1
	v_mfma_f32_16x16x32_bf16 v[54:57], v[130:133], v[172:175], v[54:57]
	v_mfma_f32_16x16x32_bf16 v[50:53], v[164:167], v[172:175], v[50:53]
	v_mfma_f32_16x16x32_bf16 v[38:41], v[130:133], v[186:189], v[38:41]
	v_mfma_f32_16x16x32_bf16 v[34:37], v[164:167], v[186:189], v[34:37]
	v_mfma_f32_16x16x32_bf16 v[22:25], v[130:133], v[194:197], v[22:25]
	v_mfma_f32_16x16x32_bf16 v[18:21], v[164:167], v[194:197], v[18:21]
	v_mfma_f32_16x16x32_bf16 v[6:9], v[130:133], v[202:205], v[6:9]
	v_mfma_f32_16x16x32_bf16 v[2:5], v[164:167], v[202:205], v[2:5]
	v_mfma_f32_16x16x32_bf16 v[54:57], v[134:137], v[176:179], v[54:57]
	v_mfma_f32_16x16x32_bf16 v[50:53], v[168:171], v[176:179], v[50:53]
	v_mfma_f32_16x16x32_bf16 v[38:41], v[134:137], v[190:193], v[38:41]
	v_mfma_f32_16x16x32_bf16 v[34:37], v[168:171], v[190:193], v[34:37]
	v_mfma_f32_16x16x32_bf16 v[22:25], v[134:137], v[198:201], v[22:25]
	v_mfma_f32_16x16x32_bf16 v[18:21], v[168:171], v[198:201], v[18:21]
	v_mfma_f32_16x16x32_bf16 v[6:9], v[134:137], v[206:209], v[6:9]
	v_mfma_f32_16x16x32_bf16 v[2:5], v[168:171], v[206:209], v[2:5]
	s_barrier
	s_setprio 0
	s_add_i32 s48, 0, 0x18000
	s_add_i32 s49, 0, 0x1c000
	v_add_u32_e32 v126, s48, v183
	v_add_u32_e32 v168, s49, v183
	ds_read_b128 v[114:117], v126
	ds_read_b128 v[118:121], v126 offset:1024
	ds_read_b128 v[122:125], v126 offset:2048
	ds_read_b128 v[126:129], v126 offset:3072
	ds_read_b128 v[130:133], v168
	ds_read_b128 v[134:137], v168 offset:1024
	ds_read_b128 v[164:167], v168 offset:2048
	ds_read_b128 v[168:171], v168 offset:3072
	s_add_u32 s26, s26, 0x40000
	s_addc_u32 s27, s27, 0
	s_mov_b32 m0, s38
	v_lshl_add_u64 v[216:217], s[26:27], 0, v[154:155]
	ds_read_b128 v[172:175], v185 offset:32768
	ds_read_b128 v[176:179], v185 offset:33792
	ds_read_b128 v[186:189], v185 offset:34816
	ds_read_b128 v[190:193], v185 offset:35840
	ds_read_b128 v[194:197], v185 offset:36864
	ds_read_b128 v[198:201], v185 offset:37888
	ds_read_b128 v[202:205], v185 offset:38912
	ds_read_b128 v[206:209], v185 offset:39936
	global_load_lds_dwordx4 v[216:217], off
	v_lshl_add_u64 v[216:217], s[26:27], 0, v[156:157]
	s_mov_b32 m0, s39
	s_nop 0
	global_load_lds_dwordx4 v[216:217], off
	s_waitcnt vmcnt(8)
	s_waitcnt lgkmcnt(0)
	s_barrier
	s_setprio 1
	s_waitcnt lgkmcnt(0)
	v_mfma_f32_16x16x32_bf16 v[150:153], v[114:117], v[172:175], v[150:153]
	v_mfma_f32_16x16x32_bf16 v[146:149], v[122:125], v[172:175], v[146:149]
	v_mfma_f32_16x16x32_bf16 v[110:113], v[114:117], v[186:189], v[110:113]
	v_mfma_f32_16x16x32_bf16 v[106:109], v[122:125], v[186:189], v[106:109]
	v_mfma_f32_16x16x32_bf16 v[94:97], v[114:117], v[194:197], v[94:97]
	v_mfma_f32_16x16x32_bf16 v[90:93], v[122:125], v[194:197], v[90:93]
	v_mfma_f32_16x16x32_bf16 v[78:81], v[114:117], v[202:205], v[78:81]
	v_mfma_f32_16x16x32_bf16 v[74:77], v[122:125], v[202:205], v[74:77]
	v_mfma_f32_16x16x32_bf16 v[150:153], v[118:121], v[176:179], v[150:153]
	v_mfma_f32_16x16x32_bf16 v[146:149], v[126:129], v[176:179], v[146:149]
	v_mfma_f32_16x16x32_bf16 v[110:113], v[118:121], v[190:193], v[110:113]
	v_mfma_f32_16x16x32_bf16 v[106:109], v[126:129], v[190:193], v[106:109]
	v_mfma_f32_16x16x32_bf16 v[94:97], v[118:121], v[198:201], v[94:97]
	v_mfma_f32_16x16x32_bf16 v[90:93], v[126:129], v[198:201], v[90:93]
	v_mfma_f32_16x16x32_bf16 v[78:81], v[118:121], v[206:209], v[78:81]
	v_mfma_f32_16x16x32_bf16 v[74:77], v[126:129], v[206:209], v[74:77]
	s_setprio 0
	s_setprio 1
	v_mfma_f32_16x16x32_bf16 v[142:145], v[130:133], v[172:175], v[142:145]
	v_mfma_f32_16x16x32_bf16 v[138:141], v[164:167], v[172:175], v[138:141]
	v_mfma_f32_16x16x32_bf16 v[102:105], v[130:133], v[186:189], v[102:105]
	v_mfma_f32_16x16x32_bf16 v[98:101], v[164:167], v[186:189], v[98:101]
	v_mfma_f32_16x16x32_bf16 v[86:89], v[130:133], v[194:197], v[86:89]
	v_mfma_f32_16x16x32_bf16 v[82:85], v[164:167], v[194:197], v[82:85]
	v_mfma_f32_16x16x32_bf16 v[70:73], v[130:133], v[202:205], v[70:73]
	v_mfma_f32_16x16x32_bf16 v[66:69], v[164:167], v[202:205], v[66:69]
	v_mfma_f32_16x16x32_bf16 v[142:145], v[134:137], v[176:179], v[142:145]
	v_mfma_f32_16x16x32_bf16 v[138:141], v[168:171], v[176:179], v[138:141]
	v_mfma_f32_16x16x32_bf16 v[102:105], v[134:137], v[190:193], v[102:105]
	v_mfma_f32_16x16x32_bf16 v[98:101], v[168:171], v[190:193], v[98:101]
	v_mfma_f32_16x16x32_bf16 v[86:89], v[134:137], v[198:201], v[86:89]
	v_mfma_f32_16x16x32_bf16 v[82:85], v[168:171], v[198:201], v[82:85]
	v_mfma_f32_16x16x32_bf16 v[70:73], v[134:137], v[206:209], v[70:73]
	v_mfma_f32_16x16x32_bf16 v[66:69], v[168:171], v[206:209], v[66:69]
	s_barrier
; #define PG8_STAGE(bufoff, gbase, voff) do { _Pragma("unroll") for (int _i = 0; _i < 2; ++_i) \
;         __builtin_amdgcn_global_load_lds((const unsigned*)((const char*)(gbase) + (voff)[_i]), (PG8_LAS unsigned*)(lds + (bufoff) + ldsw + _i * 8192), 16, 0, 0); } while (0)
; #define PG8_LDA(dst, b, h) do { _Pragma("unroll") for (int m = 0; m < 4; ++m) _Pragma("unroll") for (int k = 0; k < 2; ++k) dst[m][k] = *(const PG8_LAS bf16x8*)(lds + PG8_SA(b, h) + aoff + m * 2048 + k * 1024); } while (0)
; #define PG8_MMA(ai, bj, At, Bt) do { __builtin_amdgcn_s_setprio(1); _Pragma("unroll") for (int m = 0; m < 4; ++m) _Pragma("unroll") for (int n = 0; n < 2; ++n) _Pragma("unroll") for (int k = 0; k < 2; ++k) \
;         acc[ai][bj][m][n] = __builtin_amdgcn_mfma_f32_16x16x32_bf16(Bt[n][k], At[m][k], acc[ai][bj][m][n], 0, 0, 0); __builtin_amdgcn_s_setprio(0); } while (0)
; #define PG8_WAIT_V(n) asm volatile("s_waitcnt vmcnt(" #n ")" ::: "memory")
; #define PG8_WAIT_L(n) asm volatile("s_waitcnt lgkmcnt(" #n ")" ::: "memory")
; #define PG8_BAR __builtin_amdgcn_s_barrier()
; #define PG8_SCHED __builtin_amdgcn_sched_barrier(0)
; template <class Epi, class Sched, bool ALIGN_EPI = false, bool SP2 = false>
; __device__ __forceinline__ void gemm_phase(PG8_LAS unsigned char* lds, const Gemm g, const Sched& S, const Epi& E, const int wv) {
;     ...
;             PG8_LDA(At, 1, 1); PG8_STAGE(PG8_SB(1, 0), b3, voffB); PG8_STAGE(PG8_SB(1, 1), b3 + hstep, voffB); PG8_STAGE(PG8_SA(1, 0), a3, voffA);
;             PG8_WAIT_V(8); PG8_WAIT_L(0); PG8_BAR; PG8_MMA(1, 0, At, B0); PG8_MMA(1, 1, At, B1); PG8_BAR; PG8_SCHED;
;     ...
;         if constexpr (ALIGN_EPI) { if (wr == 0) PG8_BAR; }
	s_setprio 0
	s_add_i32 s26, s48, s36
	v_lshl_add_u64 v[180:181], v[180:181], 0, s[2:3]
	s_mov_b32 m0, s26
	ds_read_b128 v[172:175], v185 offset:49152
	ds_read_b128 v[176:179], v185 offset:50176
	ds_read_b128 v[186:189], v185 offset:51200
	ds_read_b128 v[190:193], v185 offset:52224
	ds_read_b128 v[194:197], v185 offset:53248
	ds_read_b128 v[198:201], v185 offset:54272
	ds_read_b128 v[202:205], v185 offset:55296
	ds_read_b128 v[206:209], v185 offset:56320
	global_load_lds_dwordx4 v[180:181], off
	s_add_i32 m0, s26, 0x2000
	s_add_u32 s24, s24, 0x40080
	v_lshl_add_u64 v[180:181], v[210:211], 0, s[2:3]
	s_addc_u32 s25, s25, 0
	s_add_i32 s26, s49, s36
	global_load_lds_dwordx4 v[180:181], off
	v_lshl_add_u64 v[180:181], s[24:25], 0, v[0:1]
	s_mov_b32 m0, s26
	s_nop 0
	global_load_lds_dwordx4 v[180:181], off
	v_lshl_add_u64 v[180:181], s[24:25], 0, v[158:159]
	s_add_i32 m0, s26, 0x2000
	s_nop 0
	global_load_lds_dwordx4 v[180:181], off
	v_lshl_add_u64 v[180:181], v[212:213], 0, s[2:3]
	s_mov_b32 m0, s40
	s_nop 0
	global_load_lds_dwordx4 v[180:181], off
	v_lshl_add_u64 v[180:181], v[214:215], 0, s[2:3]
	s_mov_b32 m0, s41
	s_nop 0
	global_load_lds_dwordx4 v[180:181], off
	s_waitcnt vmcnt(8)
	s_waitcnt lgkmcnt(0)
	s_barrier
	s_setprio 1
	s_waitcnt lgkmcnt(0)
	v_mfma_f32_16x16x32_bf16 v[62:65], v[114:117], v[172:175], v[62:65]
	v_mfma_f32_16x16x32_bf16 v[58:61], v[122:125], v[172:175], v[58:61]
	v_mfma_f32_16x16x32_bf16 v[46:49], v[114:117], v[186:189], v[46:49]
	v_mfma_f32_16x16x32_bf16 v[42:45], v[122:125], v[186:189], v[42:45]
	v_mfma_f32_16x16x32_bf16 v[30:33], v[114:117], v[194:197], v[30:33]
	v_mfma_f32_16x16x32_bf16 v[26:29], v[122:125], v[194:197], v[26:29]
	v_mfma_f32_16x16x32_bf16 v[14:17], v[114:117], v[202:205], v[14:17]
	v_mfma_f32_16x16x32_bf16 v[10:13], v[122:125], v[202:205], v[10:13]
	v_mfma_f32_16x16x32_bf16 v[62:65], v[118:121], v[176:179], v[62:65]
	v_mfma_f32_16x16x32_bf16 v[58:61], v[126:129], v[176:179], v[58:61]
	v_mfma_f32_16x16x32_bf16 v[46:49], v[118:121], v[190:193], v[46:49]
	v_mfma_f32_16x16x32_bf16 v[42:45], v[126:129], v[190:193], v[42:45]
	v_mfma_f32_16x16x32_bf16 v[30:33], v[118:121], v[198:201], v[30:33]
	v_mfma_f32_16x16x32_bf16 v[26:29], v[126:129], v[198:201], v[26:29]
	v_mfma_f32_16x16x32_bf16 v[14:17], v[118:121], v[206:209], v[14:17]
	v_mfma_f32_16x16x32_bf16 v[10:13], v[126:129], v[206:209], v[10:13]
	s_setprio 0
	s_setprio 1
	v_mfma_f32_16x16x32_bf16 v[54:57], v[130:133], v[172:175], v[54:57]
	v_mfma_f32_16x16x32_bf16 v[50:53], v[164:167], v[172:175], v[50:53]
	v_mfma_f32_16x16x32_bf16 v[38:41], v[130:133], v[186:189], v[38:41]
	v_mfma_f32_16x16x32_bf16 v[34:37], v[164:167], v[186:189], v[34:37]
	v_mfma_f32_16x16x32_bf16 v[22:25], v[130:133], v[194:197], v[22:25]
	v_mfma_f32_16x16x32_bf16 v[18:21], v[164:167], v[194:197], v[18:21]
	v_mfma_f32_16x16x32_bf16 v[6:9], v[130:133], v[202:205], v[6:9]
	v_mfma_f32_16x16x32_bf16 v[2:5], v[164:167], v[202:205], v[2:5]
	v_mfma_f32_16x16x32_bf16 v[54:57], v[134:137], v[176:179], v[54:57]
	v_mfma_f32_16x16x32_bf16 v[50:53], v[168:171], v[176:179], v[50:53]
	v_mfma_f32_16x16x32_bf16 v[38:41], v[134:137], v[190:193], v[38:41]
	v_mfma_f32_16x16x32_bf16 v[34:37], v[168:171], v[190:193], v[34:37]
	v_mfma_f32_16x16x32_bf16 v[22:25], v[134:137], v[198:201], v[22:25]
	v_mfma_f32_16x16x32_bf16 v[18:21], v[168:171], v[198:201], v[18:21]
	v_mfma_f32_16x16x32_bf16 v[6:9], v[134:137], v[206:209], v[6:9]
	v_mfma_f32_16x16x32_bf16 v[2:5], v[168:171], v[206:209], v[2:5]
	s_barrier
	s_setprio 0
	s_add_i32 s47, s47, 2
	s_add_u32 s22, s22, 0x100
	s_addc_u32 s23, s23, 0
	s_add_u32 s45, s45, 0x100
	s_addc_u32 s46, s46, 0
	s_cmp_gt_u32 s47, 13
	s_cbranch_scc0 .LBB0_350
	s_and_b64 vcc, exec, s[8:9]
	s_cbranch_vccz .LBB0_353
	s_barrier

; #define PG8_STAGE(bufoff, gbase, voff) do { _Pragma("unroll") for (int _i = 0; _i < 2; ++_i) \
;         __builtin_amdgcn_global_load_lds((const unsigned*)((const char*)(gbase) + (voff)[_i]), (PG8_LAS unsigned*)(lds + (bufoff) + ldsw + _i * 8192), 16, 0, 0); } while (0)
; #define PG8_LDA(dst, b, h) do { _Pragma("unroll") for (int m = 0; m < 4; ++m) _Pragma("unroll") for (int k = 0; k < 2; ++k) dst[m][k] = *(const PG8_LAS bf16x8*)(lds + PG8_SA(b, h) + aoff + m * 2048 + k * 1024); } while (0)
; #define PG8_LDB(dst, b, h) do { _Pragma("unroll") for (int n = 0; n < 2; ++n) _Pragma("unroll") for (int k = 0; k < 2; ++k) dst[n][k] = *(const PG8_LAS bf16x8*)(lds + PG8_SB(b, h) + boff + n * 2048 + k * 1024); } while (0)
; #define PG8_MMA(ai, bj, At, Bt) do { __builtin_amdgcn_s_setprio(1); _Pragma("unroll") for (int m = 0; m < 4; ++m) _Pragma("unroll") for (int n = 0; n < 2; ++n) _Pragma("unroll") for (int k = 0; k < 2; ++k) \
;         acc[ai][bj][m][n] = __builtin_amdgcn_mfma_f32_16x16x32_bf16(Bt[n][k], At[m][k], acc[ai][bj][m][n], 0, 0, 0); __builtin_amdgcn_s_setprio(0); } while (0)
; #define PG8_WAIT_V(n) asm volatile("s_waitcnt vmcnt(" #n ")" ::: "memory")
; #define PG8_WAIT_L(n) asm volatile("s_waitcnt lgkmcnt(" #n ")" ::: "memory")
; template <class Epi, class Sched, bool ALIGN_EPI = false, bool SP2 = false>
; __device__ __forceinline__ void gemm_phase(PG8_LAS unsigned char* lds, const Gemm g, const Sched& S, const Epi& E, const int wv) {
;     ...
;             const bool last = (t == nt - 2);
;             const char* a1 = cA + (size_t)(t + 1) * kstep;
;             const char* a2 = last ? nA : cA + (size_t)(t + 2) * kstep; const char* b2 = last ? nB : cB + (size_t)(t + 2) * kstep;
;             const char* a3 = a2 + kstep; const char* b3 = b2 + kstep;
;             if (last && has_next) S.a_ready(nxt);
;             if constexpr (SP2) {
;             PG8_LDB(B0, 0, 0); PG8_LDB(B1, 0, 1); PG8_SCHED; PG8_LDA(At, 0, 0); PG8_STAGE(PG8_SA(1, 1), a1 + hstep, voffA);
;             PG8_WAIT_V(8); PG8_WAIT_L(0); PG8_BAR; PG8_MMA(0, 0, At, B0); PG8_MMA(0, 1, At, B1); PG8_BAR; PG8_SCHED;
;             PG8_LDA(At, 0, 1); PG8_STAGE(PG8_SB(0, 0), b2, voffB); PG8_STAGE(PG8_SB(0, 1), b2 + hstep, voffB); PG8_STAGE(PG8_SA(0, 0), a2, voffA);
;             PG8_WAIT_V(8); PG8_WAIT_L(0); PG8_BAR; PG8_MMA(1, 0, At, B0); PG8_MMA(1, 1, At, B1); PG8_BAR; PG8_SCHED;
.LBB0_428:
	s_add_u32 s20, s18, 0xfffc0080
	s_addc_u32 s21, s19, -1
	s_add_i32 s46, 0, 0x10000
	s_cmp_eq_u32 s45, 12
	s_cselect_b32 s23, s11, s21
	s_cselect_b32 s22, s33, s20
	s_cselect_b32 s21, s9, s44
	s_cselect_b32 s20, s42, s43
	s_add_i32 s48, 0, 0x14000
	v_add_u32_e32 v152, s46, v166
	v_add_u32_e32 v164, s48, v166
	ds_read_b128 v[140:143], v152
	ds_read_b128 v[144:147], v152 offset:1024
	ds_read_b128 v[148:151], v152 offset:2048
	ds_read_b128 v[152:155], v152 offset:3072
	ds_read_b128 v[156:159], v164
	ds_read_b128 v[160:163], v164 offset:1024
	ds_read_b128 v[170:173], v164 offset:2048
	ds_read_b128 v[174:177], v164 offset:3072
	v_lshl_add_u64 v[210:211], s[18:19], 0, v[136:137]
	s_add_i32 m0, s30, 0xc000
	ds_read_b128 v[178:181], v168
	ds_read_b128 v[182:185], v168 offset:1024
	ds_read_b128 v[186:189], v168 offset:2048
	ds_read_b128 v[190:193], v168 offset:3072
	ds_read_b128 v[194:197], v168 offset:4096
	ds_read_b128 v[198:201], v168 offset:5120
	ds_read_b128 v[202:205], v168 offset:6144
	ds_read_b128 v[206:209], v168 offset:7168
	global_load_lds_dwordx4 v[210:211], off
	v_lshl_add_u64 v[210:211], s[18:19], 0, v[138:139]
	s_add_i32 m0, s30, 0xe000
	s_nop 0
	global_load_lds_dwordx4 v[210:211], off
	s_waitcnt vmcnt(8)
	s_waitcnt lgkmcnt(0)
	s_barrier
	s_setprio 1
	s_waitcnt lgkmcnt(0)
	v_mfma_f32_16x16x32_bf16 v[126:129], v[140:143], v[178:181], v[126:129]
	v_mfma_f32_16x16x32_bf16 v[118:121], v[148:151], v[178:181], v[118:121]
	v_mfma_f32_16x16x32_bf16 v[110:113], v[140:143], v[186:189], v[110:113]
	v_mfma_f32_16x16x32_bf16 v[102:105], v[148:151], v[186:189], v[102:105]
	v_mfma_f32_16x16x32_bf16 v[94:97], v[140:143], v[194:197], v[94:97]
	v_mfma_f32_16x16x32_bf16 v[86:89], v[148:151], v[194:197], v[86:89]
	v_mfma_f32_16x16x32_bf16 v[78:81], v[140:143], v[202:205], v[78:81]
	v_mfma_f32_16x16x32_bf16 v[70:73], v[148:151], v[202:205], v[70:73]
	v_mfma_f32_16x16x32_bf16 v[126:129], v[144:147], v[182:185], v[126:129]
	v_mfma_f32_16x16x32_bf16 v[118:121], v[152:155], v[182:185], v[118:121]
	v_mfma_f32_16x16x32_bf16 v[110:113], v[144:147], v[190:193], v[110:113]
	v_mfma_f32_16x16x32_bf16 v[102:105], v[152:155], v[190:193], v[102:105]
	v_mfma_f32_16x16x32_bf16 v[94:97], v[144:147], v[198:201], v[94:97]
	v_mfma_f32_16x16x32_bf16 v[86:89], v[152:155], v[198:201], v[86:89]
	v_mfma_f32_16x16x32_bf16 v[78:81], v[144:147], v[206:209], v[78:81]
	v_mfma_f32_16x16x32_bf16 v[70:73], v[152:155], v[206:209], v[70:73]
	s_setprio 0
	s_setprio 1
	v_mfma_f32_16x16x32_bf16 v[122:125], v[156:159], v[178:181], v[122:125]
	v_mfma_f32_16x16x32_bf16 v[114:117], v[170:173], v[178:181], v[114:117]
	v_mfma_f32_16x16x32_bf16 v[106:109], v[156:159], v[186:189], v[106:109]
	v_mfma_f32_16x16x32_bf16 v[98:101], v[170:173], v[186:189], v[98:101]
	v_mfma_f32_16x16x32_bf16 v[90:93], v[156:159], v[194:197], v[90:93]
	v_mfma_f32_16x16x32_bf16 v[82:85], v[170:173], v[194:197], v[82:85]
	v_mfma_f32_16x16x32_bf16 v[74:77], v[156:159], v[202:205], v[74:77]
	v_mfma_f32_16x16x32_bf16 v[66:69], v[170:173], v[202:205], v[66:69]
	v_mfma_f32_16x16x32_bf16 v[122:125], v[160:163], v[182:185], v[122:125]
	v_mfma_f32_16x16x32_bf16 v[114:117], v[174:177], v[182:185], v[114:117]
	v_mfma_f32_16x16x32_bf16 v[106:109], v[160:163], v[190:193], v[106:109]
	v_mfma_f32_16x16x32_bf16 v[98:101], v[174:177], v[190:193], v[98:101]
	v_mfma_f32_16x16x32_bf16 v[90:93], v[160:163], v[198:201], v[90:93]
	v_mfma_f32_16x16x32_bf16 v[82:85], v[174:177], v[198:201], v[82:85]
	v_mfma_f32_16x16x32_bf16 v[74:77], v[160:163], v[206:209], v[74:77]
	v_mfma_f32_16x16x32_bf16 v[66:69], v[174:177], v[206:209], v[66:69]
	s_barrier
	s_setprio 0
	s_add_i32 s46, s46, s29
	v_lshl_add_u64 v[210:211], s[20:21], 0, v[0:1]
	s_mov_b32 m0, s46
	ds_read_b128 v[178:181], v168 offset:16384
	ds_read_b128 v[182:185], v168 offset:17408
	ds_read_b128 v[186:189], v168 offset:18432
	ds_read_b128 v[190:193], v168 offset:19456
	ds_read_b128 v[194:197], v168 offset:20480
	ds_read_b128 v[198:201], v168 offset:21504
	ds_read_b128 v[202:205], v168 offset:22528
	ds_read_b128 v[206:209], v168 offset:23552
	global_load_lds_dwordx4 v[210:211], off
	s_add_i32 m0, s46, 0x2000
	s_add_u32 s46, s20, 0x40000
	v_lshl_add_u64 v[212:213], s[20:21], 0, v[130:131]
	s_addc_u32 s47, s21, 0
	s_add_i32 s48, s48, s29
	global_load_lds_dwordx4 v[212:213], off
	v_lshl_add_u64 v[214:215], s[46:47], 0, v[0:1]
	s_mov_b32 m0, s48
	v_lshl_add_u64 v[216:217], s[22:23], 0, v[132:133]
	global_load_lds_dwordx4 v[214:215], off
	v_lshl_add_u64 v[214:215], s[46:47], 0, v[130:131]
	s_add_i32 m0, s48, 0x2000
	s_nop 0
	global_load_lds_dwordx4 v[214:215], off
	v_lshl_add_u64 v[214:215], s[22:23], 0, v[134:135]
	s_mov_b32 m0, s30
	s_nop 0
	global_load_lds_dwordx4 v[214:215], off
	s_mov_b32 m0, s31
	s_nop 0
	global_load_lds_dwordx4 v[216:217], off
	s_waitcnt vmcnt(8)
	s_waitcnt lgkmcnt(0)
	s_barrier
; #define PG8_STAGE(bufoff, gbase, voff) do { _Pragma("unroll") for (int _i = 0; _i < 2; ++_i) \
;         __builtin_amdgcn_global_load_lds((const unsigned*)((const char*)(gbase) + (voff)[_i]), (PG8_LAS unsigned*)(lds + (bufoff) + ldsw + _i * 8192), 16, 0, 0); } while (0)
; #define PG8_LDA(dst, b, h) do { _Pragma("unroll") for (int m = 0; m < 4; ++m) _Pragma("unroll") for (int k = 0; k < 2; ++k) dst[m][k] = *(const PG8_LAS bf16x8*)(lds + PG8_SA(b, h) + aoff + m * 2048 + k * 1024); } while (0)
; #define PG8_LDB(dst, b, h) do { _Pragma("unroll") for (int n = 0; n < 2; ++n) _Pragma("unroll") for (int k = 0; k < 2; ++k) dst[n][k] = *(const PG8_LAS bf16x8*)(lds + PG8_SB(b, h) + boff + n * 2048 + k * 1024); } while (0)
; #define PG8_MMA(ai, bj, At, Bt) do { __builtin_amdgcn_s_setprio(1); _Pragma("unroll") for (int m = 0; m < 4; ++m) _Pragma("unroll") for (int n = 0; n < 2; ++n) _Pragma("unroll") for (int k = 0; k < 2; ++k) \
;         acc[ai][bj][m][n] = __builtin_amdgcn_mfma_f32_16x16x32_bf16(Bt[n][k], At[m][k], acc[ai][bj][m][n], 0, 0, 0); __builtin_amdgcn_s_setprio(0); } while (0)
; #define PG8_WAIT_V(n) asm volatile("s_waitcnt vmcnt(" #n ")" ::: "memory")
; #define PG8_WAIT_L(n) asm volatile("s_waitcnt lgkmcnt(" #n ")" ::: "memory")
; #define PG8_BAR __builtin_amdgcn_s_barrier()
; #define PG8_SCHED __builtin_amdgcn_sched_barrier(0)
; template <class Epi, class Sched, bool ALIGN_EPI = false, bool SP2 = false>
; __device__ __forceinline__ void gemm_phase(PG8_LAS unsigned char* lds, const Gemm g, const Sched& S, const Epi& E, const int wv) {
;     ...
;             PG8_WAIT_V(8); PG8_WAIT_L(0); PG8_BAR; PG8_MMA(1, 0, At, B0); PG8_MMA(1, 1, At, B1); PG8_BAR; PG8_SCHED;
;             PG8_LDB(B0, 1, 0); PG8_LDB(B1, 1, 1); PG8_SCHED; PG8_LDA(At, 1, 0); PG8_STAGE(PG8_SA(0, 1), a2 + hstep, voffA);
;             PG8_WAIT_V(8); PG8_WAIT_L(0); PG8_BAR; PG8_MMA(0, 0, At, B0); PG8_MMA(0, 1, At, B1); PG8_BAR; PG8_SCHED;
	s_setprio 1
	s_waitcnt lgkmcnt(0)
	v_mfma_f32_16x16x32_bf16 v[62:65], v[140:143], v[178:181], v[62:65]
	v_mfma_f32_16x16x32_bf16 v[54:57], v[148:151], v[178:181], v[54:57]
	v_mfma_f32_16x16x32_bf16 v[46:49], v[140:143], v[186:189], v[46:49]
	v_mfma_f32_16x16x32_bf16 v[38:41], v[148:151], v[186:189], v[38:41]
	v_mfma_f32_16x16x32_bf16 v[30:33], v[140:143], v[194:197], v[30:33]
	v_mfma_f32_16x16x32_bf16 v[22:25], v[148:151], v[194:197], v[22:25]
	v_mfma_f32_16x16x32_bf16 v[14:17], v[140:143], v[202:205], v[14:17]
	v_mfma_f32_16x16x32_bf16 v[6:9], v[148:151], v[202:205], v[6:9]
	v_mfma_f32_16x16x32_bf16 v[62:65], v[144:147], v[182:185], v[62:65]
	v_mfma_f32_16x16x32_bf16 v[54:57], v[152:155], v[182:185], v[54:57]
	v_mfma_f32_16x16x32_bf16 v[46:49], v[144:147], v[190:193], v[46:49]
	v_mfma_f32_16x16x32_bf16 v[38:41], v[152:155], v[190:193], v[38:41]
	v_mfma_f32_16x16x32_bf16 v[30:33], v[144:147], v[198:201], v[30:33]
	v_mfma_f32_16x16x32_bf16 v[22:25], v[152:155], v[198:201], v[22:25]
	v_mfma_f32_16x16x32_bf16 v[14:17], v[144:147], v[206:209], v[14:17]
	v_mfma_f32_16x16x32_bf16 v[6:9], v[152:155], v[206:209], v[6:9]
	s_setprio 0
	s_setprio 1
	v_mfma_f32_16x16x32_bf16 v[58:61], v[156:159], v[178:181], v[58:61]
	v_mfma_f32_16x16x32_bf16 v[50:53], v[170:173], v[178:181], v[50:53]
	v_mfma_f32_16x16x32_bf16 v[42:45], v[156:159], v[186:189], v[42:45]
	v_mfma_f32_16x16x32_bf16 v[34:37], v[170:173], v[186:189], v[34:37]
	v_mfma_f32_16x16x32_bf16 v[26:29], v[156:159], v[194:197], v[26:29]
	v_mfma_f32_16x16x32_bf16 v[18:21], v[170:173], v[194:197], v[18:21]
	v_mfma_f32_16x16x32_bf16 v[10:13], v[156:159], v[202:205], v[10:13]
	v_mfma_f32_16x16x32_bf16 v[2:5], v[170:173], v[202:205], v[2:5]
	v_mfma_f32_16x16x32_bf16 v[58:61], v[160:163], v[182:185], v[58:61]
	v_mfma_f32_16x16x32_bf16 v[50:53], v[174:177], v[182:185], v[50:53]
	v_mfma_f32_16x16x32_bf16 v[42:45], v[160:163], v[190:193], v[42:45]
	v_mfma_f32_16x16x32_bf16 v[34:37], v[174:177], v[190:193], v[34:37]
	v_mfma_f32_16x16x32_bf16 v[26:29], v[160:163], v[198:201], v[26:29]
	v_mfma_f32_16x16x32_bf16 v[18:21], v[174:177], v[198:201], v[18:21]
	v_mfma_f32_16x16x32_bf16 v[10:13], v[160:163], v[206:209], v[10:13]
	v_mfma_f32_16x16x32_bf16 v[2:5], v[174:177], v[206:209], v[2:5]
	s_barrier
	s_setprio 0
	s_add_i32 s46, 0, 0x18000
	s_add_i32 s47, 0, 0x1c000
	v_add_u32_e32 v152, s46, v166
	v_add_u32_e32 v164, s47, v166
	ds_read_b128 v[140:143], v152
	ds_read_b128 v[144:147], v152 offset:1024
	ds_read_b128 v[148:151], v152 offset:2048
	ds_read_b128 v[152:155], v152 offset:3072
	ds_read_b128 v[156:159], v164
	ds_read_b128 v[160:163], v164 offset:1024
	ds_read_b128 v[170:173], v164 offset:2048
	ds_read_b128 v[174:177], v164 offset:3072
	s_add_u32 s22, s22, 0x40000
	s_addc_u32 s23, s23, 0
	s_mov_b32 m0, s36
	v_lshl_add_u64 v[218:219], s[22:23], 0, v[134:135]
	ds_read_b128 v[178:181], v168 offset:32768
	ds_read_b128 v[182:185], v168 offset:33792
	ds_read_b128 v[186:189], v168 offset:34816
	ds_read_b128 v[190:193], v168 offset:35840
	ds_read_b128 v[194:197], v168 offset:36864
	ds_read_b128 v[198:201], v168 offset:37888
	ds_read_b128 v[202:205], v168 offset:38912
	ds_read_b128 v[206:209], v168 offset:39936
	global_load_lds_dwordx4 v[218:219], off
	v_lshl_add_u64 v[218:219], s[22:23], 0, v[132:133]
	s_mov_b32 m0, s37
	s_nop 0
	global_load_lds_dwordx4 v[218:219], off
	s_waitcnt vmcnt(8)
	s_waitcnt lgkmcnt(0)
	s_barrier
	s_setprio 1
	s_waitcnt lgkmcnt(0)
	v_mfma_f32_16x16x32_bf16 v[126:129], v[140:143], v[178:181], v[126:129]
	v_mfma_f32_16x16x32_bf16 v[118:121], v[148:151], v[178:181], v[118:121]
	v_mfma_f32_16x16x32_bf16 v[110:113], v[140:143], v[186:189], v[110:113]
	v_mfma_f32_16x16x32_bf16 v[102:105], v[148:151], v[186:189], v[102:105]
	v_mfma_f32_16x16x32_bf16 v[94:97], v[140:143], v[194:197], v[94:97]
	v_mfma_f32_16x16x32_bf16 v[86:89], v[148:151], v[194:197], v[86:89]
	v_mfma_f32_16x16x32_bf16 v[78:81], v[140:143], v[202:205], v[78:81]
	v_mfma_f32_16x16x32_bf16 v[70:73], v[148:151], v[202:205], v[70:73]
	v_mfma_f32_16x16x32_bf16 v[126:129], v[144:147], v[182:185], v[126:129]
	v_mfma_f32_16x16x32_bf16 v[118:121], v[152:155], v[182:185], v[118:121]
	v_mfma_f32_16x16x32_bf16 v[110:113], v[144:147], v[190:193], v[110:113]
	v_mfma_f32_16x16x32_bf16 v[102:105], v[152:155], v[190:193], v[102:105]
	v_mfma_f32_16x16x32_bf16 v[94:97], v[144:147], v[198:201], v[94:97]
	v_mfma_f32_16x16x32_bf16 v[86:89], v[152:155], v[198:201], v[86:89]
	v_mfma_f32_16x16x32_bf16 v[78:81], v[144:147], v[206:209], v[78:81]
	v_mfma_f32_16x16x32_bf16 v[70:73], v[152:155], v[206:209], v[70:73]
	s_setprio 0
	s_setprio 1
	v_mfma_f32_16x16x32_bf16 v[122:125], v[156:159], v[178:181], v[122:125]
	v_mfma_f32_16x16x32_bf16 v[114:117], v[170:173], v[178:181], v[114:117]
	v_mfma_f32_16x16x32_bf16 v[106:109], v[156:159], v[186:189], v[106:109]
	v_mfma_f32_16x16x32_bf16 v[98:101], v[170:173], v[186:189], v[98:101]
	v_mfma_f32_16x16x32_bf16 v[90:93], v[156:159], v[194:197], v[90:93]
	v_mfma_f32_16x16x32_bf16 v[82:85], v[170:173], v[194:197], v[82:85]
	v_mfma_f32_16x16x32_bf16 v[74:77], v[156:159], v[202:205], v[74:77]
	v_mfma_f32_16x16x32_bf16 v[66:69], v[170:173], v[202:205], v[66:69]
	v_mfma_f32_16x16x32_bf16 v[122:125], v[160:163], v[182:185], v[122:125]
	v_mfma_f32_16x16x32_bf16 v[114:117], v[174:177], v[182:185], v[114:117]
	v_mfma_f32_16x16x32_bf16 v[106:109], v[160:163], v[190:193], v[106:109]
	v_mfma_f32_16x16x32_bf16 v[98:101], v[174:177], v[190:193], v[98:101]
	v_mfma_f32_16x16x32_bf16 v[90:93], v[160:163], v[198:201], v[90:93]
	v_mfma_f32_16x16x32_bf16 v[82:85], v[174:177], v[198:201], v[82:85]
	v_mfma_f32_16x16x32_bf16 v[74:77], v[160:163], v[206:209], v[74:77]
	v_mfma_f32_16x16x32_bf16 v[66:69], v[174:177], v[206:209], v[66:69]
	s_barrier
; #define PG8_STAGE(bufoff, gbase, voff) do { _Pragma("unroll") for (int _i = 0; _i < 2; ++_i) \
;         __builtin_amdgcn_global_load_lds((const unsigned*)((const char*)(gbase) + (voff)[_i]), (PG8_LAS unsigned*)(lds + (bufoff) + ldsw + _i * 8192), 16, 0, 0); } while (0)
; #define PG8_LDA(dst, b, h) do { _Pragma("unroll") for (int m = 0; m < 4; ++m) _Pragma("unroll") for (int k = 0; k < 2; ++k) dst[m][k] = *(const PG8_LAS bf16x8*)(lds + PG8_SA(b, h) + aoff + m * 2048 + k * 1024); } while (0)
; #define PG8_MMA(ai, bj, At, Bt) do { __builtin_amdgcn_s_setprio(1); _Pragma("unroll") for (int m = 0; m < 4; ++m) _Pragma("unroll") for (int n = 0; n < 2; ++n) _Pragma("unroll") for (int k = 0; k < 2; ++k) \
;         acc[ai][bj][m][n] = __builtin_amdgcn_mfma_f32_16x16x32_bf16(Bt[n][k], At[m][k], acc[ai][bj][m][n], 0, 0, 0); __builtin_amdgcn_s_setprio(0); } while (0)
; #define PG8_WAIT_V(n) asm volatile("s_waitcnt vmcnt(" #n ")" ::: "memory")
; #define PG8_WAIT_L(n) asm volatile("s_waitcnt lgkmcnt(" #n ")" ::: "memory")
; #define PG8_BAR __builtin_amdgcn_s_barrier()
; #define PG8_SCHED __builtin_amdgcn_sched_barrier(0)
; template <class Epi, class Sched, bool ALIGN_EPI = false, bool SP2 = false>
; __device__ __forceinline__ void gemm_phase(PG8_LAS unsigned char* lds, const Gemm g, const Sched& S, const Epi& E, const int wv) {
;     ...
;             PG8_LDA(At, 1, 1); PG8_STAGE(PG8_SB(1, 0), b3, voffB); PG8_STAGE(PG8_SB(1, 1), b3 + hstep, voffB); PG8_STAGE(PG8_SA(1, 0), a3, voffA);
;             PG8_WAIT_V(8); PG8_WAIT_L(0); PG8_BAR; PG8_MMA(1, 0, At, B0); PG8_MMA(1, 1, At, B1); PG8_BAR; PG8_SCHED;
;     ...
;         if constexpr (ALIGN_EPI) { if (wr == 0) PG8_BAR; }
	s_setprio 0
	s_add_i32 s22, s46, s29
	v_lshl_add_u64 v[210:211], v[210:211], 0, s[2:3]
	s_mov_b32 m0, s22
	ds_read_b128 v[178:181], v168 offset:49152
	ds_read_b128 v[182:185], v168 offset:50176
	ds_read_b128 v[186:189], v168 offset:51200
	ds_read_b128 v[190:193], v168 offset:52224
	ds_read_b128 v[194:197], v168 offset:53248
	ds_read_b128 v[198:201], v168 offset:54272
	ds_read_b128 v[202:205], v168 offset:55296
	ds_read_b128 v[206:209], v168 offset:56320
	global_load_lds_dwordx4 v[210:211], off
	s_add_i32 m0, s22, 0x2000
	s_add_u32 s20, s20, 0x40080
	v_lshl_add_u64 v[210:211], v[212:213], 0, s[2:3]
	s_addc_u32 s21, s21, 0
	s_add_i32 s22, s47, s29
	global_load_lds_dwordx4 v[210:211], off
	v_lshl_add_u64 v[210:211], s[20:21], 0, v[0:1]
	s_mov_b32 m0, s22
	s_nop 0
	global_load_lds_dwordx4 v[210:211], off
	v_lshl_add_u64 v[210:211], s[20:21], 0, v[130:131]
	s_add_i32 m0, s22, 0x2000
	s_nop 0
	global_load_lds_dwordx4 v[210:211], off
	v_lshl_add_u64 v[210:211], v[214:215], 0, s[2:3]
	s_mov_b32 m0, s39
	s_nop 0
	global_load_lds_dwordx4 v[210:211], off
	v_lshl_add_u64 v[210:211], v[216:217], 0, s[2:3]
	s_mov_b32 m0, s40
	s_nop 0
	global_load_lds_dwordx4 v[210:211], off
	s_waitcnt vmcnt(8)
	s_waitcnt lgkmcnt(0)
	s_barrier
	s_setprio 1
	s_waitcnt lgkmcnt(0)
	v_mfma_f32_16x16x32_bf16 v[62:65], v[140:143], v[178:181], v[62:65]
	v_mfma_f32_16x16x32_bf16 v[54:57], v[148:151], v[178:181], v[54:57]
	v_mfma_f32_16x16x32_bf16 v[46:49], v[140:143], v[186:189], v[46:49]
	v_mfma_f32_16x16x32_bf16 v[38:41], v[148:151], v[186:189], v[38:41]
	v_mfma_f32_16x16x32_bf16 v[30:33], v[140:143], v[194:197], v[30:33]
	v_mfma_f32_16x16x32_bf16 v[22:25], v[148:151], v[194:197], v[22:25]
	v_mfma_f32_16x16x32_bf16 v[14:17], v[140:143], v[202:205], v[14:17]
	v_mfma_f32_16x16x32_bf16 v[6:9], v[148:151], v[202:205], v[6:9]
	v_mfma_f32_16x16x32_bf16 v[62:65], v[144:147], v[182:185], v[62:65]
	v_mfma_f32_16x16x32_bf16 v[54:57], v[152:155], v[182:185], v[54:57]
	v_mfma_f32_16x16x32_bf16 v[46:49], v[144:147], v[190:193], v[46:49]
	v_mfma_f32_16x16x32_bf16 v[38:41], v[152:155], v[190:193], v[38:41]
	v_mfma_f32_16x16x32_bf16 v[30:33], v[144:147], v[198:201], v[30:33]
	v_mfma_f32_16x16x32_bf16 v[22:25], v[152:155], v[198:201], v[22:25]
	v_mfma_f32_16x16x32_bf16 v[14:17], v[144:147], v[206:209], v[14:17]
	v_mfma_f32_16x16x32_bf16 v[6:9], v[152:155], v[206:209], v[6:9]
	s_setprio 0
	s_setprio 1
	v_mfma_f32_16x16x32_bf16 v[58:61], v[156:159], v[178:181], v[58:61]
	v_mfma_f32_16x16x32_bf16 v[50:53], v[170:173], v[178:181], v[50:53]
	v_mfma_f32_16x16x32_bf16 v[42:45], v[156:159], v[186:189], v[42:45]
	v_mfma_f32_16x16x32_bf16 v[34:37], v[170:173], v[186:189], v[34:37]
	v_mfma_f32_16x16x32_bf16 v[26:29], v[156:159], v[194:197], v[26:29]
	v_mfma_f32_16x16x32_bf16 v[18:21], v[170:173], v[194:197], v[18:21]
	v_mfma_f32_16x16x32_bf16 v[10:13], v[156:159], v[202:205], v[10:13]
	v_mfma_f32_16x16x32_bf16 v[2:5], v[170:173], v[202:205], v[2:5]
	v_mfma_f32_16x16x32_bf16 v[58:61], v[160:163], v[182:185], v[58:61]
	v_mfma_f32_16x16x32_bf16 v[50:53], v[174:177], v[182:185], v[50:53]
	v_mfma_f32_16x16x32_bf16 v[42:45], v[160:163], v[190:193], v[42:45]
	v_mfma_f32_16x16x32_bf16 v[34:37], v[174:177], v[190:193], v[34:37]
	v_mfma_f32_16x16x32_bf16 v[26:29], v[160:163], v[198:201], v[26:29]
	v_mfma_f32_16x16x32_bf16 v[18:21], v[174:177], v[198:201], v[18:21]
	v_mfma_f32_16x16x32_bf16 v[10:13], v[160:163], v[206:209], v[10:13]
	v_mfma_f32_16x16x32_bf16 v[2:5], v[174:177], v[206:209], v[2:5]
	s_barrier
	s_setprio 0
	s_add_i32 s45, s45, 2
	s_add_u32 s18, s18, 0x100
	s_addc_u32 s19, s19, 0
	s_add_u32 s43, s43, 0x100
	s_addc_u32 s44, s44, 0
	s_cmp_gt_u32 s45, 13
	s_cbranch_scc0 .LBB0_428
	s_and_b64 vcc, exec, s[6:7]
	s_cbranch_vccz .LBB0_431
	s_barrier

; #define PG8_STAGE(bufoff, gbase, voff) do { _Pragma("unroll") for (int _i = 0; _i < 2; ++_i) \
;         __builtin_amdgcn_global_load_lds((const unsigned*)((const char*)(gbase) + (voff)[_i]), (PG8_LAS unsigned*)(lds + (bufoff) + ldsw + _i * 8192), 16, 0, 0); } while (0)
; #define PG8_LDA(dst, b, h) do { _Pragma("unroll") for (int m = 0; m < 4; ++m) _Pragma("unroll") for (int k = 0; k < 2; ++k) dst[m][k] = *(const PG8_LAS bf16x8*)(lds + PG8_SA(b, h) + aoff + m * 2048 + k * 1024); } while (0)
; #define PG8_LDB(dst, b, h) do { _Pragma("unroll") for (int n = 0; n < 2; ++n) _Pragma("unroll") for (int k = 0; k < 2; ++k) dst[n][k] = *(const PG8_LAS bf16x8*)(lds + PG8_SB(b, h) + boff + n * 2048 + k * 1024); } while (0)
; #define PG8_MMA(ai, bj, At, Bt) do { __builtin_amdgcn_s_setprio(1); _Pragma("unroll") for (int m = 0; m < 4; ++m) _Pragma("unroll") for (int n = 0; n < 2; ++n) _Pragma("unroll") for (int k = 0; k < 2; ++k) \
;         acc[ai][bj][m][n] = __builtin_amdgcn_mfma_f32_16x16x32_bf16(Bt[n][k], At[m][k], acc[ai][bj][m][n], 0, 0, 0); __builtin_amdgcn_s_setprio(0); } while (0)
; #define PG8_WAIT_V(n) asm volatile("s_waitcnt vmcnt(" #n ")" ::: "memory")
; #define PG8_WAIT_L(n) asm volatile("s_waitcnt lgkmcnt(" #n ")" ::: "memory")
; template <class Epi, class Sched, bool ALIGN_EPI = false, bool SP2 = false>
; __device__ __forceinline__ void gemm_phase(PG8_LAS unsigned char* lds, const Gemm g, const Sched& S, const Epi& E, const int wv) {
;     ...
;             const bool last = (t == nt - 2);
;             const char* a1 = cA + (size_t)(t + 1) * kstep;
;             const char* a2 = last ? nA : cA + (size_t)(t + 2) * kstep; const char* b2 = last ? nB : cB + (size_t)(t + 2) * kstep;
;             const char* a3 = a2 + kstep; const char* b3 = b2 + kstep;
;             if (last && has_next) S.a_ready(nxt);
;             if constexpr (SP2) {
;             PG8_LDB(B0, 0, 0); PG8_LDB(B1, 0, 1); PG8_SCHED; PG8_LDA(At, 0, 0); PG8_STAGE(PG8_SA(1, 1), a1 + hstep, voffA);
;             PG8_WAIT_V(8); PG8_WAIT_L(0); PG8_BAR; PG8_MMA(0, 0, At, B0); PG8_MMA(0, 1, At, B1); PG8_BAR; PG8_SCHED;
;             PG8_LDA(At, 0, 1); PG8_STAGE(PG8_SB(0, 0), b2, voffB); PG8_STAGE(PG8_SB(0, 1), b2 + hstep, voffB); PG8_STAGE(PG8_SA(0, 0), a2, voffA);
;             PG8_WAIT_V(8); PG8_WAIT_L(0); PG8_BAR; PG8_MMA(1, 0, At, B0); PG8_MMA(1, 1, At, B1); PG8_BAR; PG8_SCHED;
.LBB0_504:
	s_add_u32 s10, s8, 0x100
	s_addc_u32 s11, s9, 0
	s_add_i32 s52, 0, 0x10000
	s_cmp_eq_u32 s51, 40
	s_cselect_b32 s29, s1, s11
	s_cselect_b32 s28, s0, s10
	s_cselect_b32 s27, s25, s50
	s_cselect_b32 s26, s24, s49
	s_add_i32 s53, 0, 0x14000
	v_add_u32_e32 v142, s52, v187
	v_add_u32_e32 v168, s53, v187
	ds_read_b128 v[122:125], v142
	ds_read_b128 v[130:133], v142 offset:1024
	ds_read_b128 v[138:141], v142 offset:2048
	ds_read_b128 v[142:145], v142 offset:3072
	ds_read_b128 v[146:149], v168
	ds_read_b128 v[150:153], v168 offset:1024
	ds_read_b128 v[154:157], v168 offset:2048
	ds_read_b128 v[168:171], v168 offset:3072
	v_lshl_add_u64 v[184:185], s[8:9], 0, v[164:165]
	s_add_i32 m0, s37, 0xc000
	ds_read_b128 v[172:175], v189
	ds_read_b128 v[176:179], v189 offset:1024
	ds_read_b128 v[180:183], v189 offset:2048
	ds_read_b128 v[190:193], v189 offset:3072
	ds_read_b128 v[194:197], v189 offset:4096
	ds_read_b128 v[198:201], v189 offset:5120
	ds_read_b128 v[202:205], v189 offset:6144
	ds_read_b128 v[206:209], v189 offset:7168
	global_load_lds_dwordx4 v[184:185], off
	v_lshl_add_u64 v[184:185], s[8:9], 0, v[166:167]
	s_add_i32 m0, s37, 0xe000
	s_nop 0
	global_load_lds_dwordx4 v[184:185], off
	s_waitcnt vmcnt(8)
	s_waitcnt lgkmcnt(0)
	s_barrier
	s_setprio 1
	s_waitcnt lgkmcnt(0)
	v_mfma_f32_16x16x32_bf16 v[134:137], v[122:125], v[172:175], v[134:137]
	v_mfma_f32_16x16x32_bf16 v[126:129], v[138:141], v[172:175], v[126:129]
	v_mfma_f32_16x16x32_bf16 v[110:113], v[122:125], v[180:183], v[110:113]
	v_mfma_f32_16x16x32_bf16 v[106:109], v[138:141], v[180:183], v[106:109]
	v_mfma_f32_16x16x32_bf16 v[94:97], v[122:125], v[194:197], v[94:97]
	v_mfma_f32_16x16x32_bf16 v[90:93], v[138:141], v[194:197], v[90:93]
	v_mfma_f32_16x16x32_bf16 v[78:81], v[122:125], v[202:205], v[78:81]
	v_mfma_f32_16x16x32_bf16 v[74:77], v[138:141], v[202:205], v[74:77]
	v_mfma_f32_16x16x32_bf16 v[134:137], v[130:133], v[176:179], v[134:137]
	v_mfma_f32_16x16x32_bf16 v[126:129], v[142:145], v[176:179], v[126:129]
	v_mfma_f32_16x16x32_bf16 v[110:113], v[130:133], v[190:193], v[110:113]
	v_mfma_f32_16x16x32_bf16 v[106:109], v[142:145], v[190:193], v[106:109]
	v_mfma_f32_16x16x32_bf16 v[94:97], v[130:133], v[198:201], v[94:97]
	v_mfma_f32_16x16x32_bf16 v[90:93], v[142:145], v[198:201], v[90:93]
	v_mfma_f32_16x16x32_bf16 v[78:81], v[130:133], v[206:209], v[78:81]
	v_mfma_f32_16x16x32_bf16 v[74:77], v[142:145], v[206:209], v[74:77]
	s_setprio 0
	s_setprio 1
	v_mfma_f32_16x16x32_bf16 v[118:121], v[146:149], v[172:175], v[118:121]
	v_mfma_f32_16x16x32_bf16 v[114:117], v[154:157], v[172:175], v[114:117]
	v_mfma_f32_16x16x32_bf16 v[102:105], v[146:149], v[180:183], v[102:105]
	v_mfma_f32_16x16x32_bf16 v[98:101], v[154:157], v[180:183], v[98:101]
	v_mfma_f32_16x16x32_bf16 v[86:89], v[146:149], v[194:197], v[86:89]
	v_mfma_f32_16x16x32_bf16 v[82:85], v[154:157], v[194:197], v[82:85]
	v_mfma_f32_16x16x32_bf16 v[70:73], v[146:149], v[202:205], v[70:73]
	v_mfma_f32_16x16x32_bf16 v[66:69], v[154:157], v[202:205], v[66:69]
	v_mfma_f32_16x16x32_bf16 v[118:121], v[150:153], v[176:179], v[118:121]
	v_mfma_f32_16x16x32_bf16 v[114:117], v[168:171], v[176:179], v[114:117]
	v_mfma_f32_16x16x32_bf16 v[102:105], v[150:153], v[190:193], v[102:105]
	v_mfma_f32_16x16x32_bf16 v[98:101], v[168:171], v[190:193], v[98:101]
	v_mfma_f32_16x16x32_bf16 v[86:89], v[150:153], v[198:201], v[86:89]
	v_mfma_f32_16x16x32_bf16 v[82:85], v[168:171], v[198:201], v[82:85]
	v_mfma_f32_16x16x32_bf16 v[70:73], v[150:153], v[206:209], v[70:73]
	v_mfma_f32_16x16x32_bf16 v[66:69], v[168:171], v[206:209], v[66:69]
	s_barrier
	s_setprio 0
	s_add_i32 s8, s52, s36
	v_lshl_add_u64 v[184:185], s[26:27], 0, v[0:1]
	s_mov_b32 m0, s8
	ds_read_b128 v[172:175], v189 offset:16384
	ds_read_b128 v[176:179], v189 offset:17408
	ds_read_b128 v[180:183], v189 offset:18432
	ds_read_b128 v[190:193], v189 offset:19456
	ds_read_b128 v[194:197], v189 offset:20480
	ds_read_b128 v[198:201], v189 offset:21504
	ds_read_b128 v[202:205], v189 offset:22528
	ds_read_b128 v[206:209], v189 offset:23552
	global_load_lds_dwordx4 v[184:185], off
	s_add_i32 m0, s8, 0x2000
	s_add_u32 s8, s26, 0xb0000
	v_lshl_add_u64 v[210:211], s[26:27], 0, v[162:163]
	s_addc_u32 s9, s27, 0
	s_add_i32 s52, s53, s36
	global_load_lds_dwordx4 v[210:211], off
	v_lshl_add_u64 v[212:213], s[8:9], 0, v[0:1]
	s_mov_b32 m0, s52
	v_lshl_add_u64 v[214:215], s[28:29], 0, v[160:161]
	global_load_lds_dwordx4 v[212:213], off
	v_lshl_add_u64 v[212:213], s[8:9], 0, v[162:163]
	s_add_i32 m0, s52, 0x2000
	s_nop 0
	global_load_lds_dwordx4 v[212:213], off
	v_lshl_add_u64 v[212:213], s[28:29], 0, v[158:159]
	s_mov_b32 m0, s37
	s_nop 0
	global_load_lds_dwordx4 v[212:213], off
	s_mov_b32 m0, s38
	s_nop 0
	global_load_lds_dwordx4 v[214:215], off
	s_waitcnt vmcnt(8)
	s_waitcnt lgkmcnt(0)
	s_barrier
; #define PG8_STAGE(bufoff, gbase, voff) do { _Pragma("unroll") for (int _i = 0; _i < 2; ++_i) \
;         __builtin_amdgcn_global_load_lds((const unsigned*)((const char*)(gbase) + (voff)[_i]), (PG8_LAS unsigned*)(lds + (bufoff) + ldsw + _i * 8192), 16, 0, 0); } while (0)
; #define PG8_LDA(dst, b, h) do { _Pragma("unroll") for (int m = 0; m < 4; ++m) _Pragma("unroll") for (int k = 0; k < 2; ++k) dst[m][k] = *(const PG8_LAS bf16x8*)(lds + PG8_SA(b, h) + aoff + m * 2048 + k * 1024); } while (0)
; #define PG8_LDB(dst, b, h) do { _Pragma("unroll") for (int n = 0; n < 2; ++n) _Pragma("unroll") for (int k = 0; k < 2; ++k) dst[n][k] = *(const PG8_LAS bf16x8*)(lds + PG8_SB(b, h) + boff + n * 2048 + k * 1024); } while (0)
; #define PG8_MMA(ai, bj, At, Bt) do { __builtin_amdgcn_s_setprio(1); _Pragma("unroll") for (int m = 0; m < 4; ++m) _Pragma("unroll") for (int n = 0; n < 2; ++n) _Pragma("unroll") for (int k = 0; k < 2; ++k) \
;         acc[ai][bj][m][n] = __builtin_amdgcn_mfma_f32_16x16x32_bf16(Bt[n][k], At[m][k], acc[ai][bj][m][n], 0, 0, 0); __builtin_amdgcn_s_setprio(0); } while (0)
; #define PG8_WAIT_V(n) asm volatile("s_waitcnt vmcnt(" #n ")" ::: "memory")
; #define PG8_WAIT_L(n) asm volatile("s_waitcnt lgkmcnt(" #n ")" ::: "memory")
; #define PG8_BAR __builtin_amdgcn_s_barrier()
; #define PG8_SCHED __builtin_amdgcn_sched_barrier(0)
; template <class Epi, class Sched, bool ALIGN_EPI = false, bool SP2 = false>
; __device__ __forceinline__ void gemm_phase(PG8_LAS unsigned char* lds, const Gemm g, const Sched& S, const Epi& E, const int wv) {
;     ...
;             PG8_WAIT_V(8); PG8_WAIT_L(0); PG8_BAR; PG8_MMA(1, 0, At, B0); PG8_MMA(1, 1, At, B1); PG8_BAR; PG8_SCHED;
;             PG8_LDB(B0, 1, 0); PG8_LDB(B1, 1, 1); PG8_SCHED; PG8_LDA(At, 1, 0); PG8_STAGE(PG8_SA(0, 1), a2 + hstep, voffA);
;             PG8_WAIT_V(8); PG8_WAIT_L(0); PG8_BAR; PG8_MMA(0, 0, At, B0); PG8_MMA(0, 1, At, B1); PG8_BAR; PG8_SCHED;
	s_setprio 1
	s_waitcnt lgkmcnt(0)
	v_mfma_f32_16x16x32_bf16 v[62:65], v[122:125], v[172:175], v[62:65]
	v_mfma_f32_16x16x32_bf16 v[58:61], v[138:141], v[172:175], v[58:61]
	v_mfma_f32_16x16x32_bf16 v[46:49], v[122:125], v[180:183], v[46:49]
	v_mfma_f32_16x16x32_bf16 v[42:45], v[138:141], v[180:183], v[42:45]
	v_mfma_f32_16x16x32_bf16 v[30:33], v[122:125], v[194:197], v[30:33]
	v_mfma_f32_16x16x32_bf16 v[26:29], v[138:141], v[194:197], v[26:29]
	v_mfma_f32_16x16x32_bf16 v[14:17], v[122:125], v[202:205], v[14:17]
	v_mfma_f32_16x16x32_bf16 v[10:13], v[138:141], v[202:205], v[10:13]
	v_mfma_f32_16x16x32_bf16 v[62:65], v[130:133], v[176:179], v[62:65]
	v_mfma_f32_16x16x32_bf16 v[58:61], v[142:145], v[176:179], v[58:61]
	v_mfma_f32_16x16x32_bf16 v[46:49], v[130:133], v[190:193], v[46:49]
	v_mfma_f32_16x16x32_bf16 v[42:45], v[142:145], v[190:193], v[42:45]
	v_mfma_f32_16x16x32_bf16 v[30:33], v[130:133], v[198:201], v[30:33]
	v_mfma_f32_16x16x32_bf16 v[26:29], v[142:145], v[198:201], v[26:29]
	v_mfma_f32_16x16x32_bf16 v[14:17], v[130:133], v[206:209], v[14:17]
	v_mfma_f32_16x16x32_bf16 v[10:13], v[142:145], v[206:209], v[10:13]
	s_setprio 0
	s_setprio 1
	v_mfma_f32_16x16x32_bf16 v[54:57], v[146:149], v[172:175], v[54:57]
	v_mfma_f32_16x16x32_bf16 v[50:53], v[154:157], v[172:175], v[50:53]
	v_mfma_f32_16x16x32_bf16 v[38:41], v[146:149], v[180:183], v[38:41]
	v_mfma_f32_16x16x32_bf16 v[34:37], v[154:157], v[180:183], v[34:37]
	v_mfma_f32_16x16x32_bf16 v[22:25], v[146:149], v[194:197], v[22:25]
	v_mfma_f32_16x16x32_bf16 v[18:21], v[154:157], v[194:197], v[18:21]
	v_mfma_f32_16x16x32_bf16 v[6:9], v[146:149], v[202:205], v[6:9]
	v_mfma_f32_16x16x32_bf16 v[2:5], v[154:157], v[202:205], v[2:5]
	v_mfma_f32_16x16x32_bf16 v[54:57], v[150:153], v[176:179], v[54:57]
	v_mfma_f32_16x16x32_bf16 v[50:53], v[168:171], v[176:179], v[50:53]
	v_mfma_f32_16x16x32_bf16 v[38:41], v[150:153], v[190:193], v[38:41]
	v_mfma_f32_16x16x32_bf16 v[34:37], v[168:171], v[190:193], v[34:37]
	v_mfma_f32_16x16x32_bf16 v[22:25], v[150:153], v[198:201], v[22:25]
	v_mfma_f32_16x16x32_bf16 v[18:21], v[168:171], v[198:201], v[18:21]
	v_mfma_f32_16x16x32_bf16 v[6:9], v[150:153], v[206:209], v[6:9]
	v_mfma_f32_16x16x32_bf16 v[2:5], v[168:171], v[206:209], v[2:5]
	s_barrier
	s_setprio 0
	s_add_i32 s52, 0, 0x18000
	s_add_i32 s53, 0, 0x1c000
	v_add_u32_e32 v142, s52, v187
	v_add_u32_e32 v168, s53, v187
	ds_read_b128 v[122:125], v142
	ds_read_b128 v[130:133], v142 offset:1024
	ds_read_b128 v[138:141], v142 offset:2048
	ds_read_b128 v[142:145], v142 offset:3072
	ds_read_b128 v[146:149], v168
	ds_read_b128 v[150:153], v168 offset:1024
	ds_read_b128 v[154:157], v168 offset:2048
	ds_read_b128 v[168:171], v168 offset:3072
	s_add_u32 s8, s28, 0xb0000
	s_addc_u32 s9, s29, 0
	s_mov_b32 m0, s39
	v_lshl_add_u64 v[216:217], s[8:9], 0, v[158:159]
	ds_read_b128 v[172:175], v189 offset:32768
	ds_read_b128 v[176:179], v189 offset:33792
	ds_read_b128 v[180:183], v189 offset:34816
	ds_read_b128 v[190:193], v189 offset:35840
	ds_read_b128 v[194:197], v189 offset:36864
	ds_read_b128 v[198:201], v189 offset:37888
	ds_read_b128 v[202:205], v189 offset:38912
	ds_read_b128 v[206:209], v189 offset:39936
	global_load_lds_dwordx4 v[216:217], off
	v_lshl_add_u64 v[216:217], s[8:9], 0, v[160:161]
	s_mov_b32 m0, s40
	s_nop 0
	global_load_lds_dwordx4 v[216:217], off
	s_waitcnt vmcnt(8)
	s_waitcnt lgkmcnt(0)
	s_barrier
	s_setprio 1
	s_waitcnt lgkmcnt(0)
	v_mfma_f32_16x16x32_bf16 v[134:137], v[122:125], v[172:175], v[134:137]
	v_mfma_f32_16x16x32_bf16 v[126:129], v[138:141], v[172:175], v[126:129]
	v_mfma_f32_16x16x32_bf16 v[110:113], v[122:125], v[180:183], v[110:113]
	v_mfma_f32_16x16x32_bf16 v[106:109], v[138:141], v[180:183], v[106:109]
	v_mfma_f32_16x16x32_bf16 v[94:97], v[122:125], v[194:197], v[94:97]
	v_mfma_f32_16x16x32_bf16 v[90:93], v[138:141], v[194:197], v[90:93]
	v_mfma_f32_16x16x32_bf16 v[78:81], v[122:125], v[202:205], v[78:81]
	v_mfma_f32_16x16x32_bf16 v[74:77], v[138:141], v[202:205], v[74:77]
	v_mfma_f32_16x16x32_bf16 v[134:137], v[130:133], v[176:179], v[134:137]
	v_mfma_f32_16x16x32_bf16 v[126:129], v[142:145], v[176:179], v[126:129]
	v_mfma_f32_16x16x32_bf16 v[110:113], v[130:133], v[190:193], v[110:113]
	v_mfma_f32_16x16x32_bf16 v[106:109], v[142:145], v[190:193], v[106:109]
	v_mfma_f32_16x16x32_bf16 v[94:97], v[130:133], v[198:201], v[94:97]
	v_mfma_f32_16x16x32_bf16 v[90:93], v[142:145], v[198:201], v[90:93]
	v_mfma_f32_16x16x32_bf16 v[78:81], v[130:133], v[206:209], v[78:81]
	v_mfma_f32_16x16x32_bf16 v[74:77], v[142:145], v[206:209], v[74:77]
	s_setprio 0
	s_setprio 1
	v_mfma_f32_16x16x32_bf16 v[118:121], v[146:149], v[172:175], v[118:121]
	v_mfma_f32_16x16x32_bf16 v[114:117], v[154:157], v[172:175], v[114:117]
	v_mfma_f32_16x16x32_bf16 v[102:105], v[146:149], v[180:183], v[102:105]
	v_mfma_f32_16x16x32_bf16 v[98:101], v[154:157], v[180:183], v[98:101]
	v_mfma_f32_16x16x32_bf16 v[86:89], v[146:149], v[194:197], v[86:89]
	v_mfma_f32_16x16x32_bf16 v[82:85], v[154:157], v[194:197], v[82:85]
	v_mfma_f32_16x16x32_bf16 v[70:73], v[146:149], v[202:205], v[70:73]
	v_mfma_f32_16x16x32_bf16 v[66:69], v[154:157], v[202:205], v[66:69]
	v_mfma_f32_16x16x32_bf16 v[118:121], v[150:153], v[176:179], v[118:121]
	v_mfma_f32_16x16x32_bf16 v[114:117], v[168:171], v[176:179], v[114:117]
	v_mfma_f32_16x16x32_bf16 v[102:105], v[150:153], v[190:193], v[102:105]
	v_mfma_f32_16x16x32_bf16 v[98:101], v[168:171], v[190:193], v[98:101]
	v_mfma_f32_16x16x32_bf16 v[86:89], v[150:153], v[198:201], v[86:89]
	v_mfma_f32_16x16x32_bf16 v[82:85], v[168:171], v[198:201], v[82:85]
	v_mfma_f32_16x16x32_bf16 v[70:73], v[150:153], v[206:209], v[70:73]
	v_mfma_f32_16x16x32_bf16 v[66:69], v[168:171], v[206:209], v[66:69]
	s_barrier
; #define PG8_STAGE(bufoff, gbase, voff) do { _Pragma("unroll") for (int _i = 0; _i < 2; ++_i) \
;         __builtin_amdgcn_global_load_lds((const unsigned*)((const char*)(gbase) + (voff)[_i]), (PG8_LAS unsigned*)(lds + (bufoff) + ldsw + _i * 8192), 16, 0, 0); } while (0)
; #define PG8_LDA(dst, b, h) do { _Pragma("unroll") for (int m = 0; m < 4; ++m) _Pragma("unroll") for (int k = 0; k < 2; ++k) dst[m][k] = *(const PG8_LAS bf16x8*)(lds + PG8_SA(b, h) + aoff + m * 2048 + k * 1024); } while (0)
; #define PG8_MMA(ai, bj, At, Bt) do { __builtin_amdgcn_s_setprio(1); _Pragma("unroll") for (int m = 0; m < 4; ++m) _Pragma("unroll") for (int n = 0; n < 2; ++n) _Pragma("unroll") for (int k = 0; k < 2; ++k) \
;         acc[ai][bj][m][n] = __builtin_amdgcn_mfma_f32_16x16x32_bf16(Bt[n][k], At[m][k], acc[ai][bj][m][n], 0, 0, 0); __builtin_amdgcn_s_setprio(0); } while (0)
; #define PG8_WAIT_V(n) asm volatile("s_waitcnt vmcnt(" #n ")" ::: "memory")
; #define PG8_WAIT_L(n) asm volatile("s_waitcnt lgkmcnt(" #n ")" ::: "memory")
; #define PG8_BAR __builtin_amdgcn_s_barrier()
; #define PG8_SCHED __builtin_amdgcn_sched_barrier(0)
; template <class Epi, class Sched, bool ALIGN_EPI = false, bool SP2 = false>
; __device__ __forceinline__ void gemm_phase(PG8_LAS unsigned char* lds, const Gemm g, const Sched& S, const Epi& E, const int wv) {
;     ...
;             PG8_LDA(At, 1, 1); PG8_STAGE(PG8_SB(1, 0), b3, voffB); PG8_STAGE(PG8_SB(1, 1), b3 + hstep, voffB); PG8_STAGE(PG8_SA(1, 0), a3, voffA);
;             PG8_WAIT_V(8); PG8_WAIT_L(0); PG8_BAR; PG8_MMA(1, 0, At, B0); PG8_MMA(1, 1, At, B1); PG8_BAR; PG8_SCHED;
;     ...
;         if constexpr (ALIGN_EPI) { if (wr == 0) PG8_BAR; }
	s_setprio 0
	s_add_i32 s8, s52, s36
	v_lshl_add_u64 v[184:185], v[184:185], 0, s[2:3]
	s_mov_b32 m0, s8
	ds_read_b128 v[172:175], v189 offset:49152
	ds_read_b128 v[176:179], v189 offset:50176
	ds_read_b128 v[180:183], v189 offset:51200
	ds_read_b128 v[190:193], v189 offset:52224
	ds_read_b128 v[194:197], v189 offset:53248
	ds_read_b128 v[198:201], v189 offset:54272
	ds_read_b128 v[202:205], v189 offset:55296
	ds_read_b128 v[206:209], v189 offset:56320
	global_load_lds_dwordx4 v[184:185], off
	s_add_i32 m0, s8, 0x2000
	s_add_u32 s8, s26, 0xb0080
	v_lshl_add_u64 v[184:185], v[210:211], 0, s[2:3]
	s_addc_u32 s9, s27, 0
	s_add_i32 s26, s53, s36
	global_load_lds_dwordx4 v[184:185], off
	v_lshl_add_u64 v[184:185], s[8:9], 0, v[0:1]
	s_mov_b32 m0, s26
	s_nop 0
	global_load_lds_dwordx4 v[184:185], off
	v_lshl_add_u64 v[184:185], s[8:9], 0, v[162:163]
	s_add_i32 m0, s26, 0x2000
	s_nop 0
	global_load_lds_dwordx4 v[184:185], off
	v_lshl_add_u64 v[184:185], v[212:213], 0, s[2:3]
	s_mov_b32 m0, s42
	s_nop 0
	global_load_lds_dwordx4 v[184:185], off
	v_lshl_add_u64 v[184:185], v[214:215], 0, s[2:3]
	s_mov_b32 m0, s43
	s_nop 0
	global_load_lds_dwordx4 v[184:185], off
	s_waitcnt vmcnt(8)
	s_waitcnt lgkmcnt(0)
	s_barrier
	s_setprio 1
	s_waitcnt lgkmcnt(0)
	v_mfma_f32_16x16x32_bf16 v[62:65], v[122:125], v[172:175], v[62:65]
	v_mfma_f32_16x16x32_bf16 v[58:61], v[138:141], v[172:175], v[58:61]
	v_mfma_f32_16x16x32_bf16 v[46:49], v[122:125], v[180:183], v[46:49]
	v_mfma_f32_16x16x32_bf16 v[42:45], v[138:141], v[180:183], v[42:45]
	v_mfma_f32_16x16x32_bf16 v[30:33], v[122:125], v[194:197], v[30:33]
	v_mfma_f32_16x16x32_bf16 v[26:29], v[138:141], v[194:197], v[26:29]
	v_mfma_f32_16x16x32_bf16 v[14:17], v[122:125], v[202:205], v[14:17]
	v_mfma_f32_16x16x32_bf16 v[10:13], v[138:141], v[202:205], v[10:13]
	v_mfma_f32_16x16x32_bf16 v[62:65], v[130:133], v[176:179], v[62:65]
	v_mfma_f32_16x16x32_bf16 v[58:61], v[142:145], v[176:179], v[58:61]
	v_mfma_f32_16x16x32_bf16 v[46:49], v[130:133], v[190:193], v[46:49]
	v_mfma_f32_16x16x32_bf16 v[42:45], v[142:145], v[190:193], v[42:45]
	v_mfma_f32_16x16x32_bf16 v[30:33], v[130:133], v[198:201], v[30:33]
	v_mfma_f32_16x16x32_bf16 v[26:29], v[142:145], v[198:201], v[26:29]
	v_mfma_f32_16x16x32_bf16 v[14:17], v[130:133], v[206:209], v[14:17]
	v_mfma_f32_16x16x32_bf16 v[10:13], v[142:145], v[206:209], v[10:13]
	s_setprio 0
	s_setprio 1
	v_mfma_f32_16x16x32_bf16 v[54:57], v[146:149], v[172:175], v[54:57]
	v_mfma_f32_16x16x32_bf16 v[50:53], v[154:157], v[172:175], v[50:53]
	v_mfma_f32_16x16x32_bf16 v[38:41], v[146:149], v[180:183], v[38:41]
	v_mfma_f32_16x16x32_bf16 v[34:37], v[154:157], v[180:183], v[34:37]
	v_mfma_f32_16x16x32_bf16 v[22:25], v[146:149], v[194:197], v[22:25]
	v_mfma_f32_16x16x32_bf16 v[18:21], v[154:157], v[194:197], v[18:21]
	v_mfma_f32_16x16x32_bf16 v[6:9], v[146:149], v[202:205], v[6:9]
	v_mfma_f32_16x16x32_bf16 v[2:5], v[154:157], v[202:205], v[2:5]
	v_mfma_f32_16x16x32_bf16 v[54:57], v[150:153], v[176:179], v[54:57]
	v_mfma_f32_16x16x32_bf16 v[50:53], v[168:171], v[176:179], v[50:53]
	v_mfma_f32_16x16x32_bf16 v[38:41], v[150:153], v[190:193], v[38:41]
	v_mfma_f32_16x16x32_bf16 v[34:37], v[168:171], v[190:193], v[34:37]
	v_mfma_f32_16x16x32_bf16 v[22:25], v[150:153], v[198:201], v[22:25]
	v_mfma_f32_16x16x32_bf16 v[18:21], v[168:171], v[198:201], v[18:21]
	v_mfma_f32_16x16x32_bf16 v[6:9], v[150:153], v[206:209], v[6:9]
	v_mfma_f32_16x16x32_bf16 v[2:5], v[168:171], v[206:209], v[2:5]
	s_barrier
	s_setprio 0
	s_add_i32 s51, s51, 2
	s_add_u32 s49, s49, 0x100
	s_addc_u32 s50, s50, 0
	s_cmp_gt_u32 s51, 41
	s_mov_b64 s[8:9], s[10:11]
	s_cbranch_scc0 .LBB0_504
	s_and_b64 vcc, exec, s[18:19]
	s_cbranch_vccz .LBB0_507
	s_barrier
